# GEMM K-loops: LDS waits moved in front of the barriers so every MFMA segment starts with an MFMA (lgkmcnt(8)->0 before the barrier in the B0+A segments)
# speedup vs baseline: 1.0011x; 1.0011x over previous
.LBB0_173:
	s_add_u32 s64, s62, 0x100
	s_addc_u32 s65, s63, 0
	s_add_i32 s34, 0, 0x10000
	v_add_u32_e32 v108, s34, v196
	ds_read_b128 v[96:99], v108
	ds_read_b128 v[100:103], v108 offset:1024
	ds_read_b128 v[104:107], v108 offset:2048
	ds_read_b128 v[158:161], v108 offset:3072
	s_cmp_eq_u32 s83, 28
	s_cselect_b32 s69, s57, s65
	s_cselect_b32 s68, s71, s64
	s_cselect_b32 s67, s55, s82
	s_cselect_b32 s66, s80, s81
	v_lshl_add_u64 v[108:109], s[62:63], 0, v[154:155]
	s_add_i32 m0, s44, 0xc000
	ds_read_b128 v[162:165], v207
	ds_read_b128 v[166:169], v207 offset:1024
	ds_read_b128 v[170:173], v207 offset:2048
	ds_read_b128 v[180:183], v207 offset:3072
	ds_read_b128 v[184:187], v207 offset:4096
	ds_read_b128 v[188:191], v207 offset:5120
	ds_read_b128 v[192:195], v207 offset:6144
	ds_read_b128 v[198:201], v207 offset:7168
	global_load_lds_dwordx4 v[108:109], off
	v_lshl_add_u64 v[108:109], s[62:63], 0, v[156:157]
	s_add_i32 m0, s44, 0xe000
	s_nop 0
	global_load_lds_dwordx4 v[108:109], off
	s_waitcnt lgkmcnt(0)
	s_barrier
	v_mfma_f32_16x16x32_bf16 v[138:141], v[96:99], v[162:165], v[138:141]
	v_mfma_f32_16x16x32_bf16 v[60:63], v[104:107], v[162:165], v[60:63]
	v_mfma_f32_16x16x32_bf16 v[134:137], v[96:99], v[170:173], v[134:137]
	v_mfma_f32_16x16x32_bf16 v[56:59], v[104:107], v[170:173], v[56:59]
	v_mfma_f32_16x16x32_bf16 v[130:133], v[96:99], v[184:187], v[130:133]
	v_mfma_f32_16x16x32_bf16 v[52:55], v[104:107], v[184:187], v[52:55]
	v_mfma_f32_16x16x32_bf16 v[126:129], v[96:99], v[192:195], v[126:129]
	v_mfma_f32_16x16x32_bf16 v[48:51], v[104:107], v[192:195], v[48:51]
	v_mfma_f32_16x16x32_bf16 v[138:141], v[100:103], v[166:169], v[138:141]
	v_mfma_f32_16x16x32_bf16 v[60:63], v[158:161], v[166:169], v[60:63]
	v_mfma_f32_16x16x32_bf16 v[134:137], v[100:103], v[180:183], v[134:137]
	v_mfma_f32_16x16x32_bf16 v[56:59], v[158:161], v[180:183], v[56:59]
	v_mfma_f32_16x16x32_bf16 v[130:133], v[100:103], v[188:191], v[130:133]
	v_mfma_f32_16x16x32_bf16 v[52:55], v[158:161], v[188:191], v[52:55]
	v_mfma_f32_16x16x32_bf16 v[126:129], v[100:103], v[198:201], v[126:129]
	v_mfma_f32_16x16x32_bf16 v[48:51], v[158:161], v[198:201], v[48:51]
	s_barrier
	s_add_i32 s35, 0, 0x14000
	s_add_i32 s34, s34, s39
	v_add_u32_e32 v108, s35, v196
	v_lshl_add_u64 v[174:175], s[66:67], 0, v[146:147]
	s_mov_b32 m0, s34
	ds_read_b128 v[208:211], v108
	ds_read_b128 v[212:215], v108 offset:1024
	ds_read_b128 v[216:219], v108 offset:2048
	ds_read_b128 v[220:223], v108 offset:3072
	global_load_lds_dwordx4 v[174:175], off
	v_lshl_add_u64 v[224:225], s[66:67], 0, v[142:143]
	s_add_i32 m0, s34, 0x2000
	s_nop 0
	global_load_lds_dwordx4 v[224:225], off
	s_waitcnt lgkmcnt(0)
	s_barrier
	v_mfma_f32_16x16x32_bf16 v[122:125], v[208:211], v[162:165], v[122:125]
	v_mfma_f32_16x16x32_bf16 v[44:47], v[216:219], v[162:165], v[44:47]
	v_mfma_f32_16x16x32_bf16 v[114:117], v[208:211], v[170:173], v[114:117]
	v_mfma_f32_16x16x32_bf16 v[36:39], v[216:219], v[170:173], v[36:39]
	v_mfma_f32_16x16x32_bf16 v[118:121], v[208:211], v[184:187], v[118:121]
	v_mfma_f32_16x16x32_bf16 v[40:43], v[216:219], v[184:187], v[40:43]
	v_mfma_f32_16x16x32_bf16 v[108:111], v[208:211], v[192:195], v[110:113]
	v_mfma_f32_16x16x32_bf16 v[32:35], v[216:219], v[192:195], v[32:35]
	v_mfma_f32_16x16x32_bf16 v[122:125], v[212:215], v[166:169], v[122:125]
	v_mfma_f32_16x16x32_bf16 v[44:47], v[220:223], v[166:169], v[44:47]
	v_mfma_f32_16x16x32_bf16 v[114:117], v[212:215], v[180:183], v[114:117]
	v_mfma_f32_16x16x32_bf16 v[36:39], v[220:223], v[180:183], v[36:39]
	v_mfma_f32_16x16x32_bf16 v[118:121], v[212:215], v[188:191], v[118:121]
	v_mfma_f32_16x16x32_bf16 v[40:43], v[220:223], v[188:191], v[40:43]
	v_mfma_f32_16x16x32_bf16 v[108:111], v[212:215], v[198:201], v[108:111]
	v_mfma_f32_16x16x32_bf16 v[32:35], v[220:223], v[198:201], v[32:35]
	s_mov_b32 m0, s44
	v_lshl_add_u64 v[226:227], s[68:69], 0, v[148:149]
	s_barrier
	ds_read_b128 v[162:165], v207 offset:16384
	ds_read_b128 v[166:169], v207 offset:17408
	ds_read_b128 v[170:173], v207 offset:18432
	ds_read_b128 v[180:183], v207 offset:19456
	ds_read_b128 v[184:187], v207 offset:20480
	ds_read_b128 v[188:191], v207 offset:21504
	ds_read_b128 v[192:195], v207 offset:22528
	ds_read_b128 v[198:201], v207 offset:23552
	global_load_lds_dwordx4 v[226:227], off
	v_lshl_add_u64 v[228:229], s[68:69], 0, v[144:145]
	s_mov_b32 m0, s72
	s_nop 0
	global_load_lds_dwordx4 v[228:229], off
	s_waitcnt lgkmcnt(0)
	s_barrier
	v_mfma_f32_16x16x32_bf16 v[92:95], v[96:99], v[162:165], v[92:95]
	v_mfma_f32_16x16x32_bf16 v[28:31], v[104:107], v[162:165], v[28:31]
	v_mfma_f32_16x16x32_bf16 v[88:91], v[96:99], v[170:173], v[88:91]
	v_mfma_f32_16x16x32_bf16 v[24:27], v[104:107], v[170:173], v[24:27]
	v_mfma_f32_16x16x32_bf16 v[84:87], v[96:99], v[184:187], v[84:87]
	v_mfma_f32_16x16x32_bf16 v[20:23], v[104:107], v[184:187], v[20:23]
	v_mfma_f32_16x16x32_bf16 v[80:83], v[96:99], v[192:195], v[80:83]
	v_mfma_f32_16x16x32_bf16 v[16:19], v[104:107], v[192:195], v[16:19]
	v_mfma_f32_16x16x32_bf16 v[92:95], v[100:103], v[166:169], v[92:95]
	v_mfma_f32_16x16x32_bf16 v[28:31], v[158:161], v[166:169], v[28:31]
	v_mfma_f32_16x16x32_bf16 v[88:91], v[100:103], v[180:183], v[88:91]
	v_mfma_f32_16x16x32_bf16 v[24:27], v[158:161], v[180:183], v[24:27]
	v_mfma_f32_16x16x32_bf16 v[84:87], v[100:103], v[188:191], v[84:87]
	v_mfma_f32_16x16x32_bf16 v[20:23], v[158:161], v[188:191], v[20:23]
	v_mfma_f32_16x16x32_bf16 v[80:83], v[100:103], v[198:201], v[80:83]
	v_mfma_f32_16x16x32_bf16 v[16:19], v[158:161], v[198:201], v[16:19]
	s_barrier
	s_add_u32 s62, s66, 0x80000
	s_addc_u32 s63, s67, 0
	s_add_i32 s34, s35, s39
	v_lshl_add_u64 v[96:97], s[62:63], 0, v[146:147]
	s_mov_b32 m0, s34
	s_nop 0
	global_load_lds_dwordx4 v[96:97], off
	v_lshl_add_u64 v[96:97], s[62:63], 0, v[142:143]
	s_add_i32 m0, s34, 0x2000
	s_nop 0
	global_load_lds_dwordx4 v[96:97], off
	s_waitcnt vmcnt(6)
	s_barrier
	v_mfma_f32_16x16x32_bf16 v[76:79], v[208:211], v[162:165], v[76:79]
	v_mfma_f32_16x16x32_bf16 v[12:15], v[216:219], v[162:165], v[12:15]
	v_mfma_f32_16x16x32_bf16 v[68:71], v[208:211], v[170:173], v[68:71]
	v_mfma_f32_16x16x32_bf16 v[4:7], v[216:219], v[170:173], v[4:7]
	v_mfma_f32_16x16x32_bf16 v[72:75], v[208:211], v[184:187], v[72:75]
	v_mfma_f32_16x16x32_bf16 v[8:11], v[216:219], v[184:187], v[8:11]
	v_mfma_f32_16x16x32_bf16 v[64:67], v[208:211], v[192:195], v[64:67]
	v_mfma_f32_16x16x32_bf16 v[0:3], v[216:219], v[192:195], v[0:3]
	v_mfma_f32_16x16x32_bf16 v[76:79], v[212:215], v[166:169], v[76:79]
	v_mfma_f32_16x16x32_bf16 v[12:15], v[220:223], v[166:169], v[12:15]
	v_mfma_f32_16x16x32_bf16 v[68:71], v[212:215], v[180:183], v[68:71]
	v_mfma_f32_16x16x32_bf16 v[4:7], v[220:223], v[180:183], v[4:7]
	v_mfma_f32_16x16x32_bf16 v[72:75], v[212:215], v[188:191], v[72:75]
	v_mfma_f32_16x16x32_bf16 v[8:11], v[220:223], v[188:191], v[8:11]
	v_mfma_f32_16x16x32_bf16 v[64:67], v[212:215], v[198:201], v[64:67]
	v_mfma_f32_16x16x32_bf16 v[0:3], v[220:223], v[198:201], v[0:3]
	s_add_i32 s34, 0, 0x18000
	v_add_u32_e32 v112, s34, v196
	s_barrier
	ds_read_b128 v[96:99], v112
	ds_read_b128 v[100:103], v112 offset:1024
	ds_read_b128 v[104:107], v112 offset:2048
	ds_read_b128 v[158:161], v112 offset:3072
	s_add_u32 s62, s68, 0x80000
	s_addc_u32 s63, s69, 0
	s_mov_b32 m0, s73
	v_lshl_add_u64 v[112:113], s[62:63], 0, v[148:149]
	ds_read_b128 v[162:165], v207 offset:32768
	ds_read_b128 v[166:169], v207 offset:33792
	ds_read_b128 v[170:173], v207 offset:34816
	ds_read_b128 v[180:183], v207 offset:35840
	ds_read_b128 v[184:187], v207 offset:36864
	ds_read_b128 v[188:191], v207 offset:37888
	ds_read_b128 v[192:195], v207 offset:38912
	ds_read_b128 v[198:201], v207 offset:39936
	global_load_lds_dwordx4 v[112:113], off
	v_lshl_add_u64 v[112:113], s[62:63], 0, v[144:145]
	s_mov_b32 m0, s74
	s_nop 0
	global_load_lds_dwordx4 v[112:113], off
	s_waitcnt lgkmcnt(0)
	s_barrier
	v_mfma_f32_16x16x32_bf16 v[138:141], v[96:99], v[162:165], v[138:141]
	v_mfma_f32_16x16x32_bf16 v[60:63], v[104:107], v[162:165], v[60:63]
	v_mfma_f32_16x16x32_bf16 v[134:137], v[96:99], v[170:173], v[134:137]
	v_mfma_f32_16x16x32_bf16 v[56:59], v[104:107], v[170:173], v[56:59]
	v_mfma_f32_16x16x32_bf16 v[130:133], v[96:99], v[184:187], v[130:133]
	v_mfma_f32_16x16x32_bf16 v[52:55], v[104:107], v[184:187], v[52:55]
	v_mfma_f32_16x16x32_bf16 v[126:129], v[96:99], v[192:195], v[126:129]
	v_mfma_f32_16x16x32_bf16 v[48:51], v[104:107], v[192:195], v[48:51]
	v_mfma_f32_16x16x32_bf16 v[138:141], v[100:103], v[166:169], v[138:141]
	v_mfma_f32_16x16x32_bf16 v[60:63], v[158:161], v[166:169], v[60:63]
	v_mfma_f32_16x16x32_bf16 v[134:137], v[100:103], v[180:183], v[134:137]
	v_mfma_f32_16x16x32_bf16 v[56:59], v[158:161], v[180:183], v[56:59]
	v_mfma_f32_16x16x32_bf16 v[130:133], v[100:103], v[188:191], v[130:133]
	v_mfma_f32_16x16x32_bf16 v[52:55], v[158:161], v[188:191], v[52:55]
	v_mfma_f32_16x16x32_bf16 v[126:129], v[100:103], v[198:201], v[126:129]
	v_mfma_f32_16x16x32_bf16 v[48:51], v[158:161], v[198:201], v[48:51]
	s_barrier
	s_add_i32 s35, 0, 0x1c000
	v_add_u32_e32 v112, s35, v196
	s_add_i32 s34, s34, s39
	ds_read_b128 v[208:211], v112
	ds_read_b128 v[212:215], v112 offset:1024
	ds_read_b128 v[216:219], v112 offset:2048
	ds_read_b128 v[220:223], v112 offset:3072
	v_lshl_add_u64 v[112:113], v[174:175], 0, s[40:41]
	s_mov_b32 m0, s34
	s_nop 0
	global_load_lds_dwordx4 v[112:113], off
	v_lshl_add_u64 v[112:113], v[224:225], 0, s[40:41]
	s_add_i32 m0, s34, 0x2000
	s_nop 0
	global_load_lds_dwordx4 v[112:113], off
	s_waitcnt lgkmcnt(0)
	s_barrier
	v_mfma_f32_16x16x32_bf16 v[122:125], v[208:211], v[162:165], v[122:125]
	v_mfma_f32_16x16x32_bf16 v[44:47], v[216:219], v[162:165], v[44:47]
	v_mfma_f32_16x16x32_bf16 v[112:115], v[208:211], v[170:173], v[114:117]
	v_mfma_f32_16x16x32_bf16 v[36:39], v[216:219], v[170:173], v[36:39]
	v_mfma_f32_16x16x32_bf16 v[118:121], v[208:211], v[184:187], v[118:121]
	v_mfma_f32_16x16x32_bf16 v[40:43], v[216:219], v[184:187], v[40:43]
	v_mfma_f32_16x16x32_bf16 v[108:111], v[208:211], v[192:195], v[108:111]
	v_mfma_f32_16x16x32_bf16 v[32:35], v[216:219], v[192:195], v[32:35]
	v_mfma_f32_16x16x32_bf16 v[122:125], v[212:215], v[166:169], v[122:125]
	v_mfma_f32_16x16x32_bf16 v[44:47], v[220:223], v[166:169], v[44:47]
	v_mfma_f32_16x16x32_bf16 v[114:117], v[212:215], v[180:183], v[112:115]
	v_mfma_f32_16x16x32_bf16 v[36:39], v[220:223], v[180:183], v[36:39]
	v_mfma_f32_16x16x32_bf16 v[118:121], v[212:215], v[188:191], v[118:121]
	v_mfma_f32_16x16x32_bf16 v[40:43], v[220:223], v[188:191], v[40:43]
	v_mfma_f32_16x16x32_bf16 v[110:113], v[212:215], v[198:201], v[108:111]
	v_mfma_f32_16x16x32_bf16 v[32:35], v[220:223], v[198:201], v[32:35]
	s_barrier
	s_mov_b32 m0, s76
	v_lshl_add_u64 v[108:109], v[226:227], 0, s[40:41]
	ds_read_b128 v[162:165], v207 offset:49152
	ds_read_b128 v[166:169], v207 offset:50176
	ds_read_b128 v[170:173], v207 offset:51200
	ds_read_b128 v[180:183], v207 offset:52224
	ds_read_b128 v[184:187], v207 offset:53248
	ds_read_b128 v[188:191], v207 offset:54272
	ds_read_b128 v[192:195], v207 offset:55296
	ds_read_b128 v[198:201], v207 offset:56320
	global_load_lds_dwordx4 v[108:109], off
	v_lshl_add_u64 v[108:109], v[228:229], 0, s[40:41]
	s_mov_b32 m0, s77
	s_nop 0
	global_load_lds_dwordx4 v[108:109], off
	s_waitcnt lgkmcnt(0)
	s_barrier
	v_mfma_f32_16x16x32_bf16 v[92:95], v[96:99], v[162:165], v[92:95]
	v_mfma_f32_16x16x32_bf16 v[28:31], v[104:107], v[162:165], v[28:31]
	v_mfma_f32_16x16x32_bf16 v[88:91], v[96:99], v[170:173], v[88:91]
	v_mfma_f32_16x16x32_bf16 v[24:27], v[104:107], v[170:173], v[24:27]
	v_mfma_f32_16x16x32_bf16 v[84:87], v[96:99], v[184:187], v[84:87]
	v_mfma_f32_16x16x32_bf16 v[20:23], v[104:107], v[184:187], v[20:23]
	v_mfma_f32_16x16x32_bf16 v[80:83], v[96:99], v[192:195], v[80:83]
	v_mfma_f32_16x16x32_bf16 v[16:19], v[104:107], v[192:195], v[16:19]
	v_mfma_f32_16x16x32_bf16 v[92:95], v[100:103], v[166:169], v[92:95]
	v_mfma_f32_16x16x32_bf16 v[28:31], v[158:161], v[166:169], v[28:31]
	v_mfma_f32_16x16x32_bf16 v[88:91], v[100:103], v[180:183], v[88:91]
	v_mfma_f32_16x16x32_bf16 v[24:27], v[158:161], v[180:183], v[24:27]
	v_mfma_f32_16x16x32_bf16 v[84:87], v[100:103], v[188:191], v[84:87]
	v_mfma_f32_16x16x32_bf16 v[20:23], v[158:161], v[188:191], v[20:23]
	v_mfma_f32_16x16x32_bf16 v[80:83], v[100:103], v[198:201], v[80:83]
	v_mfma_f32_16x16x32_bf16 v[16:19], v[158:161], v[198:201], v[16:19]
	s_barrier
	s_add_u32 s62, s66, 0x80080
	s_addc_u32 s63, s67, 0
	s_add_i32 s34, s35, s39
	v_lshl_add_u64 v[96:97], s[62:63], 0, v[146:147]
	s_mov_b32 m0, s34
	s_nop 0
	global_load_lds_dwordx4 v[96:97], off
	v_lshl_add_u64 v[96:97], s[62:63], 0, v[142:143]
	s_add_i32 m0, s34, 0x2000
	s_nop 0
	global_load_lds_dwordx4 v[96:97], off
	s_waitcnt vmcnt(6)
	s_barrier
	v_mfma_f32_16x16x32_bf16 v[76:79], v[208:211], v[162:165], v[76:79]
	v_mfma_f32_16x16x32_bf16 v[12:15], v[216:219], v[162:165], v[12:15]
	v_mfma_f32_16x16x32_bf16 v[68:71], v[208:211], v[170:173], v[68:71]
	v_mfma_f32_16x16x32_bf16 v[4:7], v[216:219], v[170:173], v[4:7]
	v_mfma_f32_16x16x32_bf16 v[72:75], v[208:211], v[184:187], v[72:75]
	v_mfma_f32_16x16x32_bf16 v[8:11], v[216:219], v[184:187], v[8:11]
	v_mfma_f32_16x16x32_bf16 v[64:67], v[208:211], v[192:195], v[64:67]
	v_mfma_f32_16x16x32_bf16 v[0:3], v[216:219], v[192:195], v[0:3]
	v_mfma_f32_16x16x32_bf16 v[76:79], v[212:215], v[166:169], v[76:79]
	v_mfma_f32_16x16x32_bf16 v[12:15], v[220:223], v[166:169], v[12:15]
	v_mfma_f32_16x16x32_bf16 v[68:71], v[212:215], v[180:183], v[68:71]
	v_mfma_f32_16x16x32_bf16 v[4:7], v[220:223], v[180:183], v[4:7]
	v_mfma_f32_16x16x32_bf16 v[72:75], v[212:215], v[188:191], v[72:75]
	v_mfma_f32_16x16x32_bf16 v[8:11], v[220:223], v[188:191], v[8:11]
	v_mfma_f32_16x16x32_bf16 v[64:67], v[212:215], v[198:201], v[64:67]
	v_mfma_f32_16x16x32_bf16 v[0:3], v[220:223], v[198:201], v[0:3]
	s_add_i32 s83, s83, 2
	s_add_u32 s81, s81, 0x100
	s_addc_u32 s82, s82, 0
	s_cmp_gt_u32 s83, 29
	s_mov_b64 s[62:63], s[64:65]
	s_barrier
	s_cbranch_scc0 .LBB0_173
	v_lshl_or_b32 v158, s70, 7, v150
	v_ashrrev_i32_e32 v159, 31, v158
	v_lshlrev_b64 v[96:97], 2, v[158:159]
	v_lshl_add_u64 v[98:99], s[30:31], 0, v[96:97]
	v_lshl_add_u64 v[100:101], s[46:47], 0, v[96:97]
	v_lshl_add_u64 v[102:103], s[24:25], 0, v[96:97]
	global_load_dwordx4 v[160:163], v[98:99], off
	global_load_dwordx4 v[170:173], v[100:101], off
	v_lshl_add_u64 v[98:99], s[42:43], 0, v[96:97]
	v_lshl_add_u64 v[100:101], s[48:49], 0, v[96:97]
	global_load_dwordx4 v[104:107], v[102:103], off
	global_load_dwordx4 v[164:167], v[98:99], off
	global_load_dwordx4 v[208:211], v[100:101], off
	v_lshl_add_u64 v[100:101], s[50:51], 0, v[96:97]
	global_load_dwordx4 v[212:215], v[100:101], off
	v_lshl_add_u64 v[98:99], s[26:27], 0, v[96:97]
	global_load_dwordx4 v[198:201], v[98:99], off
	v_lshl_add_u64 v[96:97], s[52:53], 0, v[96:97]
	global_load_dwordx4 v[216:219], v[96:97], off
	v_mov_b32_e32 v96, v177
	v_mov_b32_e32 v97, v177
	s_mov_b32 s62, 0xbf317218
	v_mov_b32_dpp v96, v126 row_ror:1 row_mask:0xf bank_mask:0xf
	v_mov_b32_dpp v97, v127 row_ror:1 row_mask:0xf bank_mask:0xf
	s_mov_b32 s34, 0xbfb8aa3b
	v_mov_b32_e32 v100, v177
	v_mov_b32_e32 v101, v177
	v_mov_b32_e32 v224, v177
	v_mov_b32_e32 v225, v177
	v_mov_b32_dpp v100, v138 row_ror:15 row_mask:0xf bank_mask:0xf
	v_mov_b32_dpp v101, v139 row_ror:15 row_mask:0xf bank_mask:0xf
	v_mov_b32_e32 v220, v177
	v_mov_b32_e32 v221, v177
	v_mov_b32_dpp v224, v112 row_ror:1 row_mask:0xf bank_mask:0xf
	v_mov_b32_dpp v225, v113 row_ror:1 row_mask:0xf bank_mask:0xf
	v_mov_b32_dpp v220, v128 row_ror:1 row_mask:0xf bank_mask:0xf
	v_mov_b32_dpp v221, v129 row_ror:1 row_mask:0xf bank_mask:0xf
	v_mov_b32_e32 v222, v177
	v_mov_b32_e32 v223, v177
	v_mov_b32_e32 v108, v177
	v_mov_b32_e32 v180, v177
	v_mov_b32_e32 v109, v177
	v_mov_b32_e32 v181, v177
	v_mov_b32_dpp v222, v140 row_ror:15 row_mask:0xf bank_mask:0xf
	v_mov_b32_dpp v223, v141 row_ror:15 row_mask:0xf bank_mask:0xf
	v_mov_b32_dpp v108, v110 row_ror:1 row_mask:0xf bank_mask:0xf
	v_mov_b32_dpp v180, v122 row_ror:15 row_mask:0xf bank_mask:0xf
	v_mov_b32_dpp v109, v111 row_ror:1 row_mask:0xf bank_mask:0xf
	v_mov_b32_dpp v181, v123 row_ror:15 row_mask:0xf bank_mask:0xf
	v_mov_b32_e32 v226, v177
	v_mov_b32_e32 v227, v177
	v_cmp_gt_i32_e32 vcc, 15, v151
	v_mov_b32_dpp v226, v124 row_ror:15 row_mask:0xf bank_mask:0xf
	v_mov_b32_dpp v227, v125 row_ror:15 row_mask:0xf bank_mask:0xf
	s_mov_b64 s[68:69], -1
	s_waitcnt vmcnt(0)
	v_pk_mul_f32 v[192:193], v[160:161], s[62:63] op_sel_hi:[1,0]
	v_pk_mul_f32 v[168:169], v[172:173], s[34:35] op_sel_hi:[1,0]
	v_pk_mul_f32 v[228:229], v[126:127], v[192:193]
	v_pk_mul_f32 v[194:195], v[162:163], s[62:63] op_sel_hi:[1,0]
	v_pk_mul_f32 v[186:187], v[104:105], s[62:63] op_sel_hi:[1,0]
	v_pk_mul_f32 v[188:189], v[166:167], s[62:63] op_sel_hi:[1,0]
	v_pk_mul_f32 v[172:173], v[210:211], s[34:35] op_sel_hi:[1,0]
	v_pk_mul_f32 v[96:97], v[186:187], v[96:97]
	v_pk_mul_f32 v[166:167], v[214:215], s[34:35] op_sel_hi:[1,0]
	v_pk_mul_f32 v[210:211], v[134:135], v[192:193]
	v_pk_mul_f32 v[214:215], v[130:131], v[192:193]
	v_pk_mul_f32 v[182:183], v[164:165], s[62:63] op_sel_hi:[1,0]
	v_pk_fma_f32 v[96:97], v[138:139], v[192:193], v[96:97]
	v_pk_fma_f32 v[210:211], v[138:139], v[186:187], v[210:211]
	v_pk_fma_f32 v[214:215], v[134:135], v[186:187], v[214:215]
	v_pk_fma_f32 v[228:229], v[130:131], v[186:187], v[228:229]
	v_pk_fma_f32 v[96:97], v[134:135], v[182:183], v[96:97]
	v_pk_fma_f32 v[210:211], v[130:131], v[182:183], v[210:211]
	v_pk_fma_f32 v[214:215], v[126:127], v[182:183], v[214:215]
	v_pk_fma_f32 v[100:101], v[182:183], v[100:101], v[228:229]
	v_pk_mul_f32 v[190:191], v[106:107], s[62:63] op_sel_hi:[1,0]
	v_pk_mul_f32 v[174:175], v[198:199], s[62:63] op_sel_hi:[1,0]
	v_pk_fma_f32 v[96:97], v[198:199], s[62:63], v[96:97] op_sel_hi:[1,0,1]
	v_pk_fma_f32 v[210:211], v[198:199], s[62:63], v[210:211] op_sel_hi:[1,0,1]
	v_pk_fma_f32 v[214:215], v[198:199], s[62:63], v[214:215] op_sel_hi:[1,0,1]
	v_pk_fma_f32 v[100:101], v[198:199], s[62:63], v[100:101] op_sel_hi:[1,0,1]
	v_pk_mul_f32 v[198:199], v[168:169], v[224:225]
	v_pk_mul_f32 v[164:165], v[170:171], s[34:35] op_sel_hi:[1,0]
	v_pk_mul_f32 v[170:171], v[208:209], s[34:35] op_sel_hi:[1,0]
	v_pk_mul_f32 v[162:163], v[212:213], s[34:35] op_sel_hi:[1,0]
	v_pk_mul_f32 v[104:105], v[190:191], v[220:221]
	v_pk_mul_f32 v[208:209], v[136:137], v[194:195]
	v_pk_mul_f32 v[212:213], v[132:133], v[194:195]
	v_pk_mul_f32 v[220:221], v[128:129], v[194:195]
	v_pk_fma_f32 v[198:199], v[124:125], v[172:173], v[198:199]
	v_pk_fma_f32 v[104:105], v[140:141], v[194:195], v[104:105]
	v_pk_fma_f32 v[208:209], v[140:141], v[190:191], v[208:209]
	v_pk_fma_f32 v[212:213], v[136:137], v[190:191], v[212:213]
	v_pk_fma_f32 v[220:221], v[132:133], v[190:191], v[220:221]
	v_pk_fma_f32 v[198:199], v[116:117], v[166:167], v[198:199]
	v_pk_mul_f32 v[232:233], v[110:111], v[170:171]
	v_pk_fma_f32 v[104:105], v[136:137], v[188:189], v[104:105]
	v_pk_fma_f32 v[208:209], v[132:133], v[188:189], v[208:209]
	v_pk_fma_f32 v[212:213], v[128:129], v[188:189], v[212:213]
	v_pk_fma_f32 v[220:221], v[188:189], v[222:223], v[220:221]
	v_pk_fma_f32 v[198:199], v[218:219], s[34:35], v[198:199] op_sel_hi:[1,0,1]
	v_pk_fma_f32 v[232:233], v[118:119], v[164:165], v[232:233]
	v_pk_mul_f32 v[184:185], v[200:201], s[62:63] op_sel_hi:[1,0]
	v_pk_fma_f32 v[104:105], v[200:201], s[62:63], v[104:105] op_sel_hi:[1,0,1]
	v_pk_fma_f32 v[208:209], v[200:201], s[62:63], v[208:209] op_sel_hi:[1,0,1]
	v_pk_fma_f32 v[212:213], v[200:201], s[62:63], v[212:213] op_sel_hi:[1,0,1]
	v_pk_fma_f32 v[200:201], v[200:201], s[62:63], v[220:221] op_sel_hi:[1,0,1]
	v_pk_mul_f32 v[108:109], v[164:165], v[108:109]
	v_pk_mul_f32 v[220:221], v[116:117], v[172:173]
	v_pk_mul_f32 v[222:223], v[114:115], v[170:171]
	v_pk_fma_f32 v[180:181], v[162:163], v[180:181], v[232:233]
	v_exp_f32_e32 v232, v198
	v_exp_f32_e32 v233, v199
	v_pk_fma_f32 v[108:109], v[122:123], v[170:171], v[108:109]
	v_pk_fma_f32 v[220:221], v[124:125], v[168:169], v[220:221]
	v_pk_fma_f32 v[222:223], v[122:123], v[164:165], v[222:223]
	v_pk_mul_f32 v[228:229], v[118:119], v[170:171]
	v_pk_fma_f32 v[108:109], v[114:115], v[162:163], v[108:109]
	v_pk_fma_f32 v[220:221], v[120:121], v[166:167], v[220:221]
	v_pk_fma_f32 v[222:223], v[118:119], v[162:163], v[222:223]
	v_pk_fma_f32 v[228:229], v[114:115], v[164:165], v[228:229]
	v_pk_mul_f32 v[230:231], v[112:113], v[172:173]
	v_pk_fma_f32 v[108:109], v[216:217], s[34:35], v[108:109] op_sel_hi:[1,0,1]
	v_pk_fma_f32 v[220:221], v[218:219], s[34:35], v[220:221] op_sel_hi:[1,0,1]
	v_pk_fma_f32 v[222:223], v[216:217], s[34:35], v[222:223] op_sel_hi:[1,0,1]
	v_pk_fma_f32 v[228:229], v[110:111], v[162:163], v[228:229]
	v_pk_fma_f32 v[230:231], v[120:121], v[168:169], v[230:231]
	v_pk_mul_f32 v[106:107], v[216:217], s[34:35] op_sel_hi:[1,0]
	v_pk_fma_f32 v[228:229], v[216:217], s[34:35], v[228:229] op_sel_hi:[1,0,1]
	v_pk_fma_f32 v[226:227], v[166:167], v[226:227], v[230:231]
	v_exp_f32_e32 v230, v108
	v_exp_f32_e32 v231, v109
	v_pk_fma_f32 v[180:181], v[216:217], s[34:35], v[180:181] op_sel_hi:[1,0,1]
	v_pk_add_f32 v[216:217], v[232:233], 1.0 op_sel_hi:[1,0]
	v_pk_mul_f32 v[104:105], v[104:105], v[198:199]
	v_pk_mul_f32 v[96:97], v[96:97], v[108:109]
	v_exp_f32_e32 v108, v222
	v_exp_f32_e32 v198, v220
	v_exp_f32_e32 v199, v221
	v_exp_f32_e32 v109, v223
	v_pk_mul_f32 v[224:225], v[120:121], v[172:173]
	v_rcp_f32_e32 v216, v216
	v_rcp_f32_e32 v217, v217
	v_pk_fma_f32 v[224:225], v[116:117], v[168:169], v[224:225]
	v_pk_add_f32 v[198:199], v[198:199], 1.0 op_sel_hi:[1,0]
	v_pk_fma_f32 v[224:225], v[112:113], v[166:167], v[224:225]
	v_pk_add_f32 v[108:109], v[108:109], 1.0 op_sel_hi:[1,0]
	v_pk_fma_f32 v[224:225], v[218:219], s[34:35], v[224:225] op_sel_hi:[1,0,1]
	v_pk_mul_f32 v[104:105], v[104:105], v[216:217]
	v_rcp_f32_e32 v108, v108
	v_rcp_f32_e32 v109, v109
	v_rcp_f32_e32 v198, v198
	v_rcp_f32_e32 v199, v199
	v_pk_mul_f32 v[208:209], v[208:209], v[220:221]
	v_exp_f32_e32 v216, v228
	v_exp_f32_e32 v220, v224
	v_exp_f32_e32 v221, v225
	v_exp_f32_e32 v217, v229
	v_pk_mul_f32 v[210:211], v[210:211], v[222:223]
	v_pk_mul_f32 v[160:161], v[218:219], s[34:35] op_sel_hi:[1,0]
	v_pk_fma_f32 v[218:219], v[218:219], s[34:35], v[226:227] op_sel_hi:[1,0,1]
	v_pk_mul_f32 v[198:199], v[208:209], v[198:199]
	v_pk_mul_f32 v[208:209], v[210:211], v[108:109]
	v_pk_add_f32 v[108:109], v[220:221], 1.0 op_sel_hi:[1,0]
	v_pk_add_f32 v[210:211], v[216:217], 1.0 op_sel_hi:[1,0]
	v_rcp_f32_e32 v108, v108
	v_rcp_f32_e32 v210, v210
	v_rcp_f32_e32 v211, v211
	v_rcp_f32_e32 v109, v109
	v_exp_f32_e32 v216, v180
	v_exp_f32_e32 v220, v218
	v_exp_f32_e32 v221, v219
	v_exp_f32_e32 v217, v181
	v_pk_add_f32 v[226:227], v[230:231], 1.0 op_sel_hi:[1,0]
	v_pk_mul_f32 v[212:213], v[212:213], v[224:225]
	v_pk_mul_f32 v[214:215], v[214:215], v[228:229]
	v_rcp_f32_e32 v226, v226
	v_rcp_f32_e32 v227, v227
	v_pk_mul_f32 v[212:213], v[212:213], v[108:109]
	v_pk_mul_f32 v[210:211], v[214:215], v[210:211]
	v_pk_add_f32 v[108:109], v[220:221], 1.0 op_sel_hi:[1,0]
	v_pk_add_f32 v[214:215], v[216:217], 1.0 op_sel_hi:[1,0]
	v_rcp_f32_e32 v108, v108
	v_rcp_f32_e32 v214, v214
	v_rcp_f32_e32 v109, v109
	v_rcp_f32_e32 v215, v215
	v_pk_mul_f32 v[96:97], v[96:97], v[226:227]
	v_pk_mul_f32 v[200:201], v[200:201], v[218:219]
	v_pk_mul_f32 v[100:101], v[100:101], v[180:181]
	v_pk_mul_f32 v[180:181], v[200:201], v[108:109]
	v_pk_mul_f32 v[200:201], v[100:101], v[214:215]
	v_cvt_pk_bf16_f32 v108, v96, v97
	v_cvt_pk_bf16_f32 v109, v104, v105
	v_cvt_pk_bf16_f32 v104, v208, v209
	v_cvt_pk_bf16_f32 v105, v198, v199
	v_cvt_pk_bf16_f32 v100, v210, v211
	v_cvt_pk_bf16_f32 v101, v212, v213
	s_nop 0
	v_cvt_pk_bf16_f32 v96, v200, v201
	v_cvt_pk_bf16_f32 v97, v180, v181
	s_and_saveexec_b64 s[62:63], vcc
	v_cmp_eq_u32_e32 vcc, 0, v151
	s_orn2_b64 s[68:69], vcc, exec
	s_or_b64 exec, exec, s[62:63]
	s_lshl_b32 s34, s79, 2
	s_lshl_b32 s62, s70, 8
	s_add_i32 s64, s34, s38
	s_ashr_i32 s63, s62, 31
	v_lshlrev_b32_e32 v176, 2, v150
	s_mov_b64 s[66:67], exec
	s_and_b64 s[68:69], s[66:67], s[68:69]
	v_mov_b32_e32 v198, 0xbf1f24be
	s_mov_b64 exec, s[68:69]
	s_cbranch_execz .LBB0_178
	s_ashr_i32 s65, s64, 31
	s_lshl_b64 s[68:69], s[64:65], 2
	v_or_b32_e32 v178, s68, v152
	v_mov_b64_e32 v[180:181], s[4:5]
	s_mov_b32 s29, 0xb000
	v_mad_u64_u32 v[180:181], s[70:71], v178, s29, v[180:181]
	v_mad_i32_i24 v181, s69, v204, v181
	v_lshl_add_u64 v[180:181], s[62:63], 2, v[180:181]
	v_lshl_add_u64 v[180:181], v[180:181], 0, v[176:177]
	v_cndmask_b32_e64 v133, v133, v141, s[8:9]
	v_cndmask_b32_e64 v132, v132, v140, s[8:9]
	v_cndmask_b32_e64 v131, v131, v139, s[8:9]
	v_cndmask_b32_e64 v130, v130, v138, s[8:9]
	v_cndmask_b32_e64 v118, v118, v122, s[8:9]
	v_cndmask_b32_e64 v121, v121, v125, s[8:9]
	v_cndmask_b32_e64 v120, v120, v124, s[8:9]
	v_cndmask_b32_e64 v119, v119, v123, s[8:9]
	global_store_dwordx4 v[180:181], v[130:133], off
	global_store_dwordx4 v[180:181], v[118:121], off offset:512
	v_cndmask_b32_e64 v125, v129, v137, s[8:9]
	v_cndmask_b32_e64 v124, v128, v136, s[8:9]
	v_add_co_u32_e32 v118, vcc, s29, v180
	v_cndmask_b32_e64 v123, v127, v135, s[8:9]
	v_cndmask_b32_e64 v122, v126, v134, s[8:9]
	v_addc_co_u32_e32 v119, vcc, 0, v181, vcc
	v_cndmask_b32_e64 v113, v113, v117, s[8:9]
	v_cndmask_b32_e64 v112, v112, v116, s[8:9]
	v_cndmask_b32_e64 v111, v111, v115, s[8:9]
	v_cndmask_b32_e64 v110, v110, v114, s[8:9]
	global_store_dwordx4 v[118:119], v[122:125], off
	global_store_dwordx4 v[118:119], v[110:113], off offset:512

.LBB0_264:
	s_add_i32 s61, s24, 2
	s_add_u32 s26, s8, 0x80
	s_addc_u32 s25, s9, 0
	s_add_i32 s29, 0, 0x10000
	v_add_u32_e32 v140, s29, v193
	ds_read_b128 v[128:131], v140
	ds_read_b128 v[132:135], v140 offset:1024
	ds_read_b128 v[136:139], v140 offset:2048
	ds_read_b128 v[140:143], v140 offset:3072
	s_cmp_eq_u32 s47, s24
	s_cselect_b32 s24, s20, s26
	s_cselect_b32 s25, s21, s25
	s_cselect_b32 s27, s11, s60
	s_cselect_b32 s26, s10, s59
	v_lshl_add_u64 v[180:181], s[8:9], 0, v[174:175]
	s_add_i32 m0, s33, 0xc000
	ds_read_b128 v[144:147], v195
	ds_read_b128 v[148:151], v195 offset:1024
	ds_read_b128 v[152:155], v195 offset:2048
	ds_read_b128 v[156:159], v195 offset:3072
	ds_read_b128 v[160:163], v195 offset:4096
	ds_read_b128 v[164:167], v195 offset:5120
	ds_read_b128 v[184:187], v195 offset:6144
	ds_read_b128 v[188:191], v195 offset:7168
	global_load_lds_dwordx4 v[180:181], off
	v_lshl_add_u64 v[180:181], s[8:9], 0, v[182:183]
	s_add_i32 m0, s33, 0xe000
	s_nop 0
	global_load_lds_dwordx4 v[180:181], off
	s_waitcnt lgkmcnt(0)
	s_barrier
	v_mfma_f32_16x16x32_bf16 v[124:127], v[128:131], v[144:147], v[124:127]
	v_mfma_f32_16x16x32_bf16 v[120:123], v[136:139], v[144:147], v[120:123]
	v_mfma_f32_16x16x32_bf16 v[108:111], v[128:131], v[152:155], v[108:111]
	v_mfma_f32_16x16x32_bf16 v[104:107], v[136:139], v[152:155], v[104:107]
	v_mfma_f32_16x16x32_bf16 v[92:95], v[128:131], v[160:163], v[92:95]
	v_mfma_f32_16x16x32_bf16 v[88:91], v[136:139], v[160:163], v[88:91]
	v_mfma_f32_16x16x32_bf16 v[76:79], v[128:131], v[184:187], v[76:79]
	v_mfma_f32_16x16x32_bf16 v[72:75], v[136:139], v[184:187], v[72:75]
	v_mfma_f32_16x16x32_bf16 v[124:127], v[132:135], v[148:151], v[124:127]
	v_mfma_f32_16x16x32_bf16 v[120:123], v[140:143], v[148:151], v[120:123]
	v_mfma_f32_16x16x32_bf16 v[108:111], v[132:135], v[156:159], v[108:111]
	v_mfma_f32_16x16x32_bf16 v[104:107], v[140:143], v[156:159], v[104:107]
	v_mfma_f32_16x16x32_bf16 v[92:95], v[132:135], v[164:167], v[92:95]
	v_mfma_f32_16x16x32_bf16 v[88:91], v[140:143], v[164:167], v[88:91]
	v_mfma_f32_16x16x32_bf16 v[76:79], v[132:135], v[188:191], v[76:79]
	v_mfma_f32_16x16x32_bf16 v[72:75], v[140:143], v[188:191], v[72:75]
	s_barrier
	s_add_i32 s34, 0, 0x14000
	s_add_i32 s29, s29, s31
	v_add_u32_e32 v178, s34, v193
	v_lshl_add_u64 v[180:181], s[26:27], 0, v[176:177]
	s_mov_b32 m0, s29
	ds_read_b128 v[196:199], v178
	ds_read_b128 v[208:211], v178 offset:1024
	ds_read_b128 v[212:215], v178 offset:2048
	ds_read_b128 v[216:219], v178 offset:3072
	global_load_lds_dwordx4 v[180:181], off
	v_lshl_add_u64 v[200:201], s[26:27], 0, v[168:169]
	s_add_i32 m0, s29, 0x2000
	s_nop 0
	global_load_lds_dwordx4 v[200:201], off
	s_waitcnt lgkmcnt(0)
	s_barrier
	v_mfma_f32_16x16x32_bf16 v[116:119], v[196:199], v[144:147], v[116:119]
	v_mfma_f32_16x16x32_bf16 v[112:115], v[212:215], v[144:147], v[112:115]
	v_mfma_f32_16x16x32_bf16 v[100:103], v[196:199], v[152:155], v[100:103]
	v_mfma_f32_16x16x32_bf16 v[96:99], v[212:215], v[152:155], v[96:99]
	v_mfma_f32_16x16x32_bf16 v[84:87], v[196:199], v[160:163], v[84:87]
	v_mfma_f32_16x16x32_bf16 v[80:83], v[212:215], v[160:163], v[80:83]
	v_mfma_f32_16x16x32_bf16 v[68:71], v[196:199], v[184:187], v[68:71]
	v_mfma_f32_16x16x32_bf16 v[64:67], v[212:215], v[184:187], v[64:67]
	v_mfma_f32_16x16x32_bf16 v[116:119], v[208:211], v[148:151], v[116:119]
	v_mfma_f32_16x16x32_bf16 v[112:115], v[216:219], v[148:151], v[112:115]
	v_mfma_f32_16x16x32_bf16 v[100:103], v[208:211], v[156:159], v[100:103]
	v_mfma_f32_16x16x32_bf16 v[96:99], v[216:219], v[156:159], v[96:99]
	v_mfma_f32_16x16x32_bf16 v[84:87], v[208:211], v[164:167], v[84:87]
	v_mfma_f32_16x16x32_bf16 v[80:83], v[216:219], v[164:167], v[80:83]
	v_mfma_f32_16x16x32_bf16 v[68:71], v[208:211], v[188:191], v[68:71]
	v_mfma_f32_16x16x32_bf16 v[64:67], v[216:219], v[188:191], v[64:67]
	s_mov_b32 m0, s33
	v_lshl_add_u64 v[220:221], s[24:25], 0, v[172:173]
	s_barrier
	ds_read_b128 v[144:147], v195 offset:16384
	ds_read_b128 v[148:151], v195 offset:17408
	ds_read_b128 v[152:155], v195 offset:18432
	ds_read_b128 v[156:159], v195 offset:19456
	ds_read_b128 v[160:163], v195 offset:20480
	ds_read_b128 v[164:167], v195 offset:21504
	ds_read_b128 v[184:187], v195 offset:22528
	ds_read_b128 v[188:191], v195 offset:23552
	global_load_lds_dwordx4 v[220:221], off
	v_lshl_add_u64 v[222:223], s[24:25], 0, v[170:171]
	s_mov_b32 m0, s37
	s_nop 0
	global_load_lds_dwordx4 v[222:223], off
	s_waitcnt lgkmcnt(0)
	s_barrier
	v_mfma_f32_16x16x32_bf16 v[60:63], v[128:131], v[144:147], v[60:63]
	v_mfma_f32_16x16x32_bf16 v[56:59], v[136:139], v[144:147], v[56:59]
	v_mfma_f32_16x16x32_bf16 v[44:47], v[128:131], v[152:155], v[44:47]
	v_mfma_f32_16x16x32_bf16 v[40:43], v[136:139], v[152:155], v[40:43]
	v_mfma_f32_16x16x32_bf16 v[28:31], v[128:131], v[160:163], v[28:31]
	v_mfma_f32_16x16x32_bf16 v[24:27], v[136:139], v[160:163], v[24:27]
	v_mfma_f32_16x16x32_bf16 v[12:15], v[128:131], v[184:187], v[12:15]
	v_mfma_f32_16x16x32_bf16 v[8:11], v[136:139], v[184:187], v[8:11]
	v_mfma_f32_16x16x32_bf16 v[60:63], v[132:135], v[148:151], v[60:63]
	v_mfma_f32_16x16x32_bf16 v[56:59], v[140:143], v[148:151], v[56:59]
	v_mfma_f32_16x16x32_bf16 v[44:47], v[132:135], v[156:159], v[44:47]
	v_mfma_f32_16x16x32_bf16 v[40:43], v[140:143], v[156:159], v[40:43]
	v_mfma_f32_16x16x32_bf16 v[28:31], v[132:135], v[164:167], v[28:31]
	v_mfma_f32_16x16x32_bf16 v[24:27], v[140:143], v[164:167], v[24:27]
	v_mfma_f32_16x16x32_bf16 v[12:15], v[132:135], v[188:191], v[12:15]
	v_mfma_f32_16x16x32_bf16 v[8:11], v[140:143], v[188:191], v[8:11]
	s_barrier
	s_add_u32 s26, s26, s44
	s_addc_u32 s27, s27, 0
	s_add_i32 s29, s34, s31
	v_lshl_add_u64 v[224:225], s[26:27], 0, v[176:177]
	s_mov_b32 m0, s29
	v_lshl_add_u64 v[226:227], s[26:27], 0, v[168:169]
	global_load_lds_dwordx4 v[224:225], off
	s_add_i32 m0, s29, 0x2000
	s_nop 0
	global_load_lds_dwordx4 v[226:227], off
	s_waitcnt vmcnt(6)
	s_barrier
	v_mfma_f32_16x16x32_bf16 v[52:55], v[196:199], v[144:147], v[52:55]
	v_mfma_f32_16x16x32_bf16 v[48:51], v[212:215], v[144:147], v[48:51]
	v_mfma_f32_16x16x32_bf16 v[36:39], v[196:199], v[152:155], v[36:39]
	v_mfma_f32_16x16x32_bf16 v[32:35], v[212:215], v[152:155], v[32:35]
	v_mfma_f32_16x16x32_bf16 v[20:23], v[196:199], v[160:163], v[20:23]
	v_mfma_f32_16x16x32_bf16 v[16:19], v[212:215], v[160:163], v[16:19]
	v_mfma_f32_16x16x32_bf16 v[4:7], v[196:199], v[184:187], v[4:7]
	v_mfma_f32_16x16x32_bf16 v[0:3], v[212:215], v[184:187], v[0:3]
	v_mfma_f32_16x16x32_bf16 v[52:55], v[208:211], v[148:151], v[52:55]
	v_mfma_f32_16x16x32_bf16 v[48:51], v[216:219], v[148:151], v[48:51]
	v_mfma_f32_16x16x32_bf16 v[36:39], v[208:211], v[156:159], v[36:39]
	v_mfma_f32_16x16x32_bf16 v[32:35], v[216:219], v[156:159], v[32:35]
	v_mfma_f32_16x16x32_bf16 v[20:23], v[208:211], v[164:167], v[20:23]
	v_mfma_f32_16x16x32_bf16 v[16:19], v[216:219], v[164:167], v[16:19]
	v_mfma_f32_16x16x32_bf16 v[4:7], v[208:211], v[188:191], v[4:7]
	v_mfma_f32_16x16x32_bf16 v[0:3], v[216:219], v[188:191], v[0:3]
	s_add_i32 s26, 0, 0x18000
	v_add_u32_e32 v140, s26, v193
	s_barrier
	ds_read_b128 v[128:131], v140
	ds_read_b128 v[132:135], v140 offset:1024
	ds_read_b128 v[136:139], v140 offset:2048
	ds_read_b128 v[140:143], v140 offset:3072
	s_add_u32 s24, s24, s44
	s_addc_u32 s25, s25, 0
	s_mov_b32 m0, s38
	v_lshl_add_u64 v[196:197], s[24:25], 0, v[172:173]
	ds_read_b128 v[144:147], v195 offset:32768
	ds_read_b128 v[148:151], v195 offset:33792
	ds_read_b128 v[152:155], v195 offset:34816
	ds_read_b128 v[156:159], v195 offset:35840
	ds_read_b128 v[160:163], v195 offset:36864
	ds_read_b128 v[164:167], v195 offset:37888
	ds_read_b128 v[184:187], v195 offset:38912
	ds_read_b128 v[188:191], v195 offset:39936
	global_load_lds_dwordx4 v[196:197], off
	v_lshl_add_u64 v[196:197], s[24:25], 0, v[170:171]
	s_mov_b32 m0, s39
	s_nop 0
	global_load_lds_dwordx4 v[196:197], off
	s_waitcnt lgkmcnt(0)
	s_barrier
	v_mfma_f32_16x16x32_bf16 v[124:127], v[128:131], v[144:147], v[124:127]
	v_mfma_f32_16x16x32_bf16 v[120:123], v[136:139], v[144:147], v[120:123]
	v_mfma_f32_16x16x32_bf16 v[108:111], v[128:131], v[152:155], v[108:111]
	v_mfma_f32_16x16x32_bf16 v[104:107], v[136:139], v[152:155], v[104:107]
	v_mfma_f32_16x16x32_bf16 v[92:95], v[128:131], v[160:163], v[92:95]
	v_mfma_f32_16x16x32_bf16 v[88:91], v[136:139], v[160:163], v[88:91]
	v_mfma_f32_16x16x32_bf16 v[76:79], v[128:131], v[184:187], v[76:79]
	v_mfma_f32_16x16x32_bf16 v[72:75], v[136:139], v[184:187], v[72:75]
	v_mfma_f32_16x16x32_bf16 v[124:127], v[132:135], v[148:151], v[124:127]
	v_mfma_f32_16x16x32_bf16 v[120:123], v[140:143], v[148:151], v[120:123]
	v_mfma_f32_16x16x32_bf16 v[108:111], v[132:135], v[156:159], v[108:111]
	v_mfma_f32_16x16x32_bf16 v[104:107], v[140:143], v[156:159], v[104:107]
	v_mfma_f32_16x16x32_bf16 v[92:95], v[132:135], v[164:167], v[92:95]
	v_mfma_f32_16x16x32_bf16 v[88:91], v[140:143], v[164:167], v[88:91]
	v_mfma_f32_16x16x32_bf16 v[76:79], v[132:135], v[188:191], v[76:79]
	v_mfma_f32_16x16x32_bf16 v[72:75], v[140:143], v[188:191], v[72:75]
	s_barrier
	s_add_i32 s24, 0, 0x1c000
	s_add_i32 s25, s26, s31
	v_add_u32_e32 v178, s24, v193
	v_lshl_add_u64 v[180:181], v[180:181], 0, s[40:41]
	s_mov_b32 m0, s25
	ds_read_b128 v[196:199], v178
	ds_read_b128 v[208:211], v178 offset:1024
	ds_read_b128 v[212:215], v178 offset:2048
	ds_read_b128 v[216:219], v178 offset:3072
	global_load_lds_dwordx4 v[180:181], off
	v_lshl_add_u64 v[180:181], v[200:201], 0, s[40:41]
	s_add_i32 m0, s25, 0x2000
	s_nop 0
	global_load_lds_dwordx4 v[180:181], off
	s_waitcnt lgkmcnt(0)
	s_barrier
	v_mfma_f32_16x16x32_bf16 v[116:119], v[196:199], v[144:147], v[116:119]
	v_mfma_f32_16x16x32_bf16 v[112:115], v[212:215], v[144:147], v[112:115]
	v_mfma_f32_16x16x32_bf16 v[100:103], v[196:199], v[152:155], v[100:103]
	v_mfma_f32_16x16x32_bf16 v[96:99], v[212:215], v[152:155], v[96:99]
	v_mfma_f32_16x16x32_bf16 v[84:87], v[196:199], v[160:163], v[84:87]
	v_mfma_f32_16x16x32_bf16 v[80:83], v[212:215], v[160:163], v[80:83]
	v_mfma_f32_16x16x32_bf16 v[68:71], v[196:199], v[184:187], v[68:71]
	v_mfma_f32_16x16x32_bf16 v[64:67], v[212:215], v[184:187], v[64:67]
	v_mfma_f32_16x16x32_bf16 v[116:119], v[208:211], v[148:151], v[116:119]
	v_mfma_f32_16x16x32_bf16 v[112:115], v[216:219], v[148:151], v[112:115]
	v_mfma_f32_16x16x32_bf16 v[100:103], v[208:211], v[156:159], v[100:103]
	v_mfma_f32_16x16x32_bf16 v[96:99], v[216:219], v[156:159], v[96:99]
	v_mfma_f32_16x16x32_bf16 v[84:87], v[208:211], v[164:167], v[84:87]
	v_mfma_f32_16x16x32_bf16 v[80:83], v[216:219], v[164:167], v[80:83]
	v_mfma_f32_16x16x32_bf16 v[68:71], v[208:211], v[188:191], v[68:71]
	v_mfma_f32_16x16x32_bf16 v[64:67], v[216:219], v[188:191], v[64:67]
	s_mov_b32 m0, s43
	v_lshl_add_u64 v[180:181], v[220:221], 0, s[40:41]
	s_barrier
	ds_read_b128 v[144:147], v195 offset:49152
	ds_read_b128 v[148:151], v195 offset:50176
	ds_read_b128 v[152:155], v195 offset:51200
	ds_read_b128 v[156:159], v195 offset:52224
	ds_read_b128 v[160:163], v195 offset:53248
	ds_read_b128 v[164:167], v195 offset:54272
	ds_read_b128 v[184:187], v195 offset:55296
	ds_read_b128 v[188:191], v195 offset:56320
	global_load_lds_dwordx4 v[180:181], off
	v_lshl_add_u64 v[180:181], v[222:223], 0, s[40:41]
	s_mov_b32 m0, s46
	s_nop 0
	global_load_lds_dwordx4 v[180:181], off
	s_waitcnt lgkmcnt(0)
	s_barrier
	v_mfma_f32_16x16x32_bf16 v[60:63], v[128:131], v[144:147], v[60:63]
	v_mfma_f32_16x16x32_bf16 v[56:59], v[136:139], v[144:147], v[56:59]
	v_mfma_f32_16x16x32_bf16 v[44:47], v[128:131], v[152:155], v[44:47]
	v_mfma_f32_16x16x32_bf16 v[40:43], v[136:139], v[152:155], v[40:43]
	v_mfma_f32_16x16x32_bf16 v[28:31], v[128:131], v[160:163], v[28:31]
	v_mfma_f32_16x16x32_bf16 v[24:27], v[136:139], v[160:163], v[24:27]
	v_mfma_f32_16x16x32_bf16 v[12:15], v[128:131], v[184:187], v[12:15]
	v_mfma_f32_16x16x32_bf16 v[8:11], v[136:139], v[184:187], v[8:11]
	v_mfma_f32_16x16x32_bf16 v[60:63], v[132:135], v[148:151], v[60:63]
	v_mfma_f32_16x16x32_bf16 v[56:59], v[140:143], v[148:151], v[56:59]
	v_mfma_f32_16x16x32_bf16 v[44:47], v[132:135], v[156:159], v[44:47]
	v_mfma_f32_16x16x32_bf16 v[40:43], v[140:143], v[156:159], v[40:43]
	v_mfma_f32_16x16x32_bf16 v[28:31], v[132:135], v[164:167], v[28:31]
	v_mfma_f32_16x16x32_bf16 v[24:27], v[140:143], v[164:167], v[24:27]
	v_mfma_f32_16x16x32_bf16 v[12:15], v[132:135], v[188:191], v[12:15]
	v_mfma_f32_16x16x32_bf16 v[8:11], v[140:143], v[188:191], v[8:11]
	s_barrier
	s_add_i32 s24, s24, s31
	v_lshl_add_u64 v[128:129], v[224:225], 0, s[40:41]
	s_mov_b32 m0, s24
	s_nop 0
	global_load_lds_dwordx4 v[128:129], off
	v_lshl_add_u64 v[128:129], v[226:227], 0, s[40:41]
	s_add_i32 m0, s24, 0x2000
	s_nop 0
	global_load_lds_dwordx4 v[128:129], off
	s_waitcnt vmcnt(6)
	s_barrier
	v_mfma_f32_16x16x32_bf16 v[52:55], v[196:199], v[144:147], v[52:55]
	v_mfma_f32_16x16x32_bf16 v[48:51], v[212:215], v[144:147], v[48:51]
	v_mfma_f32_16x16x32_bf16 v[36:39], v[196:199], v[152:155], v[36:39]
	v_mfma_f32_16x16x32_bf16 v[32:35], v[212:215], v[152:155], v[32:35]
	v_mfma_f32_16x16x32_bf16 v[20:23], v[196:199], v[160:163], v[20:23]
	v_mfma_f32_16x16x32_bf16 v[16:19], v[212:215], v[160:163], v[16:19]
	v_mfma_f32_16x16x32_bf16 v[4:7], v[196:199], v[184:187], v[4:7]
	v_mfma_f32_16x16x32_bf16 v[0:3], v[212:215], v[184:187], v[0:3]
	v_mfma_f32_16x16x32_bf16 v[52:55], v[208:211], v[148:151], v[52:55]
	v_mfma_f32_16x16x32_bf16 v[48:51], v[216:219], v[148:151], v[48:51]
	v_mfma_f32_16x16x32_bf16 v[36:39], v[208:211], v[156:159], v[36:39]
	v_mfma_f32_16x16x32_bf16 v[32:35], v[216:219], v[156:159], v[32:35]
	v_mfma_f32_16x16x32_bf16 v[20:23], v[208:211], v[164:167], v[20:23]
	v_mfma_f32_16x16x32_bf16 v[16:19], v[216:219], v[164:167], v[16:19]
	v_mfma_f32_16x16x32_bf16 v[4:7], v[208:211], v[188:191], v[4:7]
	v_mfma_f32_16x16x32_bf16 v[0:3], v[216:219], v[188:191], v[0:3]
	s_add_u32 s59, s59, 0x100
	s_addc_u32 s60, s60, 0
	s_add_u32 s8, s8, 0x100
	s_addc_u32 s9, s9, 0
	s_cmp_ge_u32 s61, s42
	s_mov_b32 s24, s61
	s_barrier
	s_cbranch_scc0 .LBB0_264
	s_sub_i32 s8, s57, 32
	s_lshr_b32 s8, s8, 3
	s_cmp_lt_i32 s57, 32
	s_cselect_b32 s26, 8, s8
	v_readlane_b32 s8, v255, 40
	v_readlane_b32 s9, v255, 41
	s_load_dwordx16 s[60:75], s[8:9], 0x0
	v_lshl_or_b32 v184, s58, 8, v194
	v_ashrrev_i32_e32 v185, 31, v184
	v_lshlrev_b64 v[128:129], 2, v[184:185]
	v_lshl_add_u32 v186, s57, 8, v192
	s_waitcnt lgkmcnt(0)
	s_cselect_b32 s24, s60, s50
	s_cselect_b32 s25, s61, s51
	s_add_i32 s8, s26, s53
	s_mul_hi_u32 s9, s8, 0xc000
	s_mul_i32 s8, s8, 0xc000
	s_add_u32 s8, s48, s8
	s_addc_u32 s9, s49, s9
	s_add_i32 s26, s54, s26
	s_mul_hi_u32 s27, s26, 0xc000
	s_mul_i32 s26, s26, 0xc000
	s_add_u32 s26, s48, s26
	s_addc_u32 s27, s49, s27
	v_lshl_add_u64 v[132:133], s[8:9], 0, v[128:129]
	v_lshl_add_u64 v[140:141], s[26:27], 0, v[128:129]
	global_load_dwordx4 v[144:147], v[132:133], off offset:16
	global_load_dwordx4 v[152:155], v[132:133], off
	global_load_dwordx4 v[148:151], v[140:141], off offset:16
	global_load_dwordx4 v[156:159], v[140:141], off
	global_load_dwordx4 v[128:131], v[132:133], off offset:528
	global_load_dwordx4 v[136:139], v[132:133], off offset:512
	s_nop 0
	global_load_dwordx4 v[132:135], v[140:141], off offset:528
	s_nop 0
	global_load_dwordx4 v[140:143], v[140:141], off offset:512
	v_lshl_add_u32 v196, v186, 11, v184
	v_lshlrev_b32_e32 v197, 2, v196
	v_lshlrev_b32_e32 v196, 1, v196
	s_and_b64 vcc, exec, s[4:5]
	s_cbranch_vccnz .Lres_f32
	global_load_dwordx4 v[164:167], v196, s[12:13]
	global_load_dwordx4 v[184:187], v196, s[12:13] offset:256
	s_add_u32 s62, s12, 0x10000
	s_addc_u32 s63, s13, 0
	global_load_dwordx4 v[188:191], v196, s[62:63]
	s_add_u32 s62, s12, 0x10000
	s_addc_u32 s63, s13, 0
	global_load_dwordx4 v[208:211], v196, s[62:63] offset:256
	s_add_u32 s62, s12, 0x20000
	s_addc_u32 s63, s13, 0
	global_load_dwordx4 v[212:215], v196, s[62:63]
	s_add_u32 s62, s12, 0x20000
	s_addc_u32 s63, s13, 0
	global_load_dwordx4 v[216:219], v196, s[62:63] offset:256
	s_add_u32 s62, s12, 0x30000
	s_addc_u32 s63, s13, 0
	global_load_dwordx4 v[220:223], v196, s[62:63]
	s_add_u32 s62, s12, 0x30000
	s_addc_u32 s63, s13, 0
	global_load_dwordx4 v[224:227], v196, s[62:63] offset:256
	s_waitcnt vmcnt(8)
	v_pk_add_f32 v[146:147], v[146:147], v[150:151]
	v_pk_add_f32 v[144:145], v[144:145], v[148:149]
	v_pk_add_f32 v[154:155], v[154:155], v[158:159]
	v_pk_add_f32 v[152:153], v[152:153], v[156:157]
	v_pk_add_f32 v[136:137], v[136:137], v[140:141]
	v_pk_add_f32 v[130:131], v[130:131], v[134:135]
	v_pk_add_f32 v[128:129], v[128:129], v[132:133]
	v_pk_add_f32 v[138:139], v[138:139], v[142:143]
	s_add_u32 s62, s12, 0x80000
	s_addc_u32 s63, s13, 0
	global_load_dwordx4 v[148:151], v196, s[62:63]
	s_add_u32 s62, s12, 0x80000
	s_addc_u32 s63, s13, 0
	global_load_dwordx4 v[156:159], v196, s[62:63] offset:256
	s_add_u32 s62, s12, 0x90000
	s_addc_u32 s63, s13, 0
	global_load_dwordx4 v[132:135], v196, s[62:63]
	s_add_u32 s62, s12, 0x90000
	s_addc_u32 s63, s13, 0
	global_load_dwordx4 v[140:143], v196, s[62:63] offset:256
	s_waitcnt vmcnt(11)
	v_lshlrev_b32_e32 v160, 16, v164
	v_and_b32_e32 v161, 0xffff0000, v164
	v_lshlrev_b32_e32 v162, 16, v165
	v_and_b32_e32 v163, 0xffff0000, v165
	v_lshlrev_b32_e32 v164, 16, v166
	v_and_b32_e32 v165, 0xffff0000, v166
	v_lshlrev_b32_e32 v166, 16, v167
	v_and_b32_e32 v167, 0xffff0000, v167
	v_pk_fma_f32 v[124:125], v[124:125], v[152:153], v[160:161]
	v_pk_fma_f32 v[126:127], v[126:127], v[154:155], v[162:163]
	v_pk_fma_f32 v[120:121], v[120:121], v[144:145], v[164:165]
	v_pk_fma_f32 v[122:123], v[122:123], v[146:147], v[166:167]
	s_add_u32 s62, s12, 0xa0000
	s_addc_u32 s63, s13, 0
	global_load_dwordx4 v[164:167], v196, s[62:63]
	v_cvt_pk_bf16_f32 v124, v124, v125
	v_cvt_pk_bf16_f32 v125, v126, v127
	v_cvt_pk_bf16_f32 v126, v120, v121
	v_cvt_pk_bf16_f32 v127, v122, v123
	global_store_dwordx4 v196, v[124:127], s[12:13]
	s_waitcnt vmcnt(12)
	v_lshlrev_b32_e32 v160, 16, v184
	v_and_b32_e32 v161, 0xffff0000, v184
	v_lshlrev_b32_e32 v162, 16, v185
	v_and_b32_e32 v163, 0xffff0000, v185
	v_lshlrev_b32_e32 v184, 16, v186
	v_and_b32_e32 v185, 0xffff0000, v186
	v_lshlrev_b32_e32 v186, 16, v187
	v_and_b32_e32 v187, 0xffff0000, v187
	v_pk_fma_f32 v[116:117], v[116:117], v[136:137], v[160:161]
	v_pk_fma_f32 v[118:119], v[118:119], v[138:139], v[162:163]
	v_pk_fma_f32 v[112:113], v[112:113], v[128:129], v[184:185]
	v_pk_fma_f32 v[114:115], v[114:115], v[130:131], v[186:187]
	s_add_u32 s62, s12, 0xa0000
	s_addc_u32 s63, s13, 0
	global_load_dwordx4 v[184:187], v196, s[62:63] offset:256
	v_cvt_pk_bf16_f32 v116, v116, v117
	v_cvt_pk_bf16_f32 v117, v118, v119
	v_cvt_pk_bf16_f32 v118, v112, v113
	v_cvt_pk_bf16_f32 v119, v114, v115
	global_store_dwordx4 v196, v[116:119], s[12:13] offset:256
	s_waitcnt vmcnt(13)
	v_lshlrev_b32_e32 v160, 16, v188
	v_and_b32_e32 v161, 0xffff0000, v188
	v_lshlrev_b32_e32 v162, 16, v189
	v_and_b32_e32 v163, 0xffff0000, v189
	v_lshlrev_b32_e32 v188, 16, v190
	v_and_b32_e32 v189, 0xffff0000, v190
	v_lshlrev_b32_e32 v190, 16, v191
	v_and_b32_e32 v191, 0xffff0000, v191
	v_pk_fma_f32 v[108:109], v[108:109], v[152:153], v[160:161]
	v_pk_fma_f32 v[110:111], v[110:111], v[154:155], v[162:163]
	v_pk_fma_f32 v[104:105], v[104:105], v[144:145], v[188:189]
	v_pk_fma_f32 v[106:107], v[106:107], v[146:147], v[190:191]
	s_add_u32 s62, s12, 0xb0000
	s_addc_u32 s63, s13, 0
	global_load_dwordx4 v[188:191], v196, s[62:63]
	v_cvt_pk_bf16_f32 v108, v108, v109
	v_cvt_pk_bf16_f32 v109, v110, v111
	v_cvt_pk_bf16_f32 v110, v104, v105
	v_cvt_pk_bf16_f32 v111, v106, v107
	s_add_u32 s64, s12, 0x10000
	s_addc_u32 s65, s13, 0
	global_store_dwordx4 v196, v[108:111], s[64:65]
	s_waitcnt vmcnt(14)
	v_lshlrev_b32_e32 v160, 16, v208
	v_and_b32_e32 v161, 0xffff0000, v208
	v_lshlrev_b32_e32 v162, 16, v209
	v_and_b32_e32 v163, 0xffff0000, v209
	v_lshlrev_b32_e32 v208, 16, v210
	v_and_b32_e32 v209, 0xffff0000, v210
	v_lshlrev_b32_e32 v210, 16, v211
	v_and_b32_e32 v211, 0xffff0000, v211
	v_pk_fma_f32 v[100:101], v[100:101], v[136:137], v[160:161]
	v_pk_fma_f32 v[102:103], v[102:103], v[138:139], v[162:163]
	v_pk_fma_f32 v[96:97], v[96:97], v[128:129], v[208:209]
	v_pk_fma_f32 v[98:99], v[98:99], v[130:131], v[210:211]
	s_add_u32 s62, s12, 0xb0000
	s_addc_u32 s63, s13, 0
	global_load_dwordx4 v[208:211], v196, s[62:63] offset:256
	v_cvt_pk_bf16_f32 v100, v100, v101
	v_cvt_pk_bf16_f32 v101, v102, v103
	v_cvt_pk_bf16_f32 v102, v96, v97
	v_cvt_pk_bf16_f32 v103, v98, v99
	s_add_u32 s64, s12, 0x10000
	s_addc_u32 s65, s13, 0
	global_store_dwordx4 v196, v[100:103], s[64:65] offset:256
	s_waitcnt vmcnt(15)
	v_lshlrev_b32_e32 v160, 16, v212
	v_and_b32_e32 v161, 0xffff0000, v212
	v_lshlrev_b32_e32 v162, 16, v213
	v_and_b32_e32 v163, 0xffff0000, v213
	v_lshlrev_b32_e32 v212, 16, v214
	v_and_b32_e32 v213, 0xffff0000, v214
	v_lshlrev_b32_e32 v214, 16, v215
	v_and_b32_e32 v215, 0xffff0000, v215
	v_pk_fma_f32 v[92:93], v[92:93], v[152:153], v[160:161]
	v_pk_fma_f32 v[94:95], v[94:95], v[154:155], v[162:163]
	v_pk_fma_f32 v[88:89], v[88:89], v[144:145], v[212:213]
	v_pk_fma_f32 v[90:91], v[90:91], v[146:147], v[214:215]
	v_cvt_pk_bf16_f32 v92, v92, v93
	v_cvt_pk_bf16_f32 v93, v94, v95
	v_cvt_pk_bf16_f32 v94, v88, v89
	v_cvt_pk_bf16_f32 v95, v90, v91
	s_add_u32 s64, s12, 0x20000
	s_addc_u32 s65, s13, 0
	global_store_dwordx4 v196, v[92:95], s[64:65]
	s_waitcnt vmcnt(15)
	v_lshlrev_b32_e32 v160, 16, v216
	v_and_b32_e32 v161, 0xffff0000, v216
	v_lshlrev_b32_e32 v162, 16, v217
	v_and_b32_e32 v163, 0xffff0000, v217
	v_lshlrev_b32_e32 v216, 16, v218
	v_and_b32_e32 v217, 0xffff0000, v218
	v_lshlrev_b32_e32 v218, 16, v219
	v_and_b32_e32 v219, 0xffff0000, v219
	v_pk_fma_f32 v[84:85], v[84:85], v[136:137], v[160:161]
	v_pk_fma_f32 v[86:87], v[86:87], v[138:139], v[162:163]
	v_pk_fma_f32 v[80:81], v[80:81], v[128:129], v[216:217]
	v_pk_fma_f32 v[82:83], v[82:83], v[130:131], v[218:219]
	v_cvt_pk_bf16_f32 v84, v84, v85
	v_cvt_pk_bf16_f32 v85, v86, v87
	v_cvt_pk_bf16_f32 v86, v80, v81
	v_cvt_pk_bf16_f32 v87, v82, v83
	s_add_u32 s64, s12, 0x20000
	s_addc_u32 s65, s13, 0
	global_store_dwordx4 v196, v[84:87], s[64:65] offset:256
	s_waitcnt vmcnt(15)
	v_lshlrev_b32_e32 v160, 16, v220
	v_and_b32_e32 v161, 0xffff0000, v220
	v_lshlrev_b32_e32 v162, 16, v221
	v_and_b32_e32 v163, 0xffff0000, v221
	v_lshlrev_b32_e32 v220, 16, v222
	v_and_b32_e32 v221, 0xffff0000, v222
	v_lshlrev_b32_e32 v222, 16, v223
	v_and_b32_e32 v223, 0xffff0000, v223
	v_pk_fma_f32 v[76:77], v[76:77], v[152:153], v[160:161]
	v_pk_fma_f32 v[78:79], v[78:79], v[154:155], v[162:163]
	v_pk_fma_f32 v[72:73], v[72:73], v[144:145], v[220:221]
	v_pk_fma_f32 v[74:75], v[74:75], v[146:147], v[222:223]
	v_cvt_pk_bf16_f32 v76, v76, v77
	v_cvt_pk_bf16_f32 v77, v78, v79
	v_cvt_pk_bf16_f32 v78, v72, v73
	v_cvt_pk_bf16_f32 v79, v74, v75
	s_add_u32 s64, s12, 0x30000
	s_addc_u32 s65, s13, 0
	global_store_dwordx4 v196, v[76:79], s[64:65]
	s_waitcnt vmcnt(15)
	v_lshlrev_b32_e32 v160, 16, v224
	v_and_b32_e32 v161, 0xffff0000, v224
	v_lshlrev_b32_e32 v162, 16, v225
	v_and_b32_e32 v163, 0xffff0000, v225
	v_lshlrev_b32_e32 v224, 16, v226
	v_and_b32_e32 v225, 0xffff0000, v226
	v_lshlrev_b32_e32 v226, 16, v227
	v_and_b32_e32 v227, 0xffff0000, v227
	v_pk_fma_f32 v[68:69], v[68:69], v[136:137], v[160:161]
	v_pk_fma_f32 v[70:71], v[70:71], v[138:139], v[162:163]
	v_pk_fma_f32 v[64:65], v[64:65], v[128:129], v[224:225]
	v_pk_fma_f32 v[66:67], v[66:67], v[130:131], v[226:227]
	v_cvt_pk_bf16_f32 v68, v68, v69
	v_cvt_pk_bf16_f32 v69, v70, v71
	v_cvt_pk_bf16_f32 v70, v64, v65
	v_cvt_pk_bf16_f32 v71, v66, v67
	s_add_u32 s64, s12, 0x30000
	s_addc_u32 s65, s13, 0
	global_store_dwordx4 v196, v[68:71], s[64:65] offset:256
	s_waitcnt vmcnt(15)
	v_lshlrev_b32_e32 v160, 16, v148
	v_and_b32_e32 v161, 0xffff0000, v148
	v_lshlrev_b32_e32 v162, 16, v149
	v_and_b32_e32 v163, 0xffff0000, v149
	v_lshlrev_b32_e32 v148, 16, v150
	v_and_b32_e32 v149, 0xffff0000, v150
	v_lshlrev_b32_e32 v150, 16, v151
	v_and_b32_e32 v151, 0xffff0000, v151
	v_pk_fma_f32 v[60:61], v[60:61], v[152:153], v[160:161]
	v_pk_fma_f32 v[62:63], v[62:63], v[154:155], v[162:163]
	v_pk_fma_f32 v[56:57], v[56:57], v[144:145], v[148:149]
	v_pk_fma_f32 v[58:59], v[58:59], v[146:147], v[150:151]
	v_cvt_pk_bf16_f32 v60, v60, v61
	v_cvt_pk_bf16_f32 v61, v62, v63
	v_cvt_pk_bf16_f32 v62, v56, v57
	v_cvt_pk_bf16_f32 v63, v58, v59
	s_add_u32 s64, s12, 0x80000
	s_addc_u32 s65, s13, 0
	global_store_dwordx4 v196, v[60:63], s[64:65]
	s_waitcnt vmcnt(15)
	v_lshlrev_b32_e32 v160, 16, v156
	v_and_b32_e32 v161, 0xffff0000, v156
	v_lshlrev_b32_e32 v162, 16, v157
	v_and_b32_e32 v163, 0xffff0000, v157
	v_lshlrev_b32_e32 v156, 16, v158
	v_and_b32_e32 v157, 0xffff0000, v158
	v_lshlrev_b32_e32 v158, 16, v159
	v_and_b32_e32 v159, 0xffff0000, v159
	v_pk_fma_f32 v[52:53], v[52:53], v[136:137], v[160:161]
	v_pk_fma_f32 v[54:55], v[54:55], v[138:139], v[162:163]
	v_pk_fma_f32 v[48:49], v[48:49], v[128:129], v[156:157]
	v_pk_fma_f32 v[50:51], v[50:51], v[130:131], v[158:159]
	v_cvt_pk_bf16_f32 v52, v52, v53
	v_cvt_pk_bf16_f32 v53, v54, v55
	v_cvt_pk_bf16_f32 v54, v48, v49
	v_cvt_pk_bf16_f32 v55, v50, v51
	s_add_u32 s64, s12, 0x80000
	s_addc_u32 s65, s13, 0
	global_store_dwordx4 v196, v[52:55], s[64:65] offset:256
	s_waitcnt vmcnt(15)
	v_lshlrev_b32_e32 v160, 16, v132
	v_and_b32_e32 v161, 0xffff0000, v132
	v_lshlrev_b32_e32 v162, 16, v133
	v_and_b32_e32 v163, 0xffff0000, v133
	v_lshlrev_b32_e32 v132, 16, v134
	v_and_b32_e32 v133, 0xffff0000, v134
	v_lshlrev_b32_e32 v134, 16, v135
	v_and_b32_e32 v135, 0xffff0000, v135
	v_pk_fma_f32 v[44:45], v[44:45], v[152:153], v[160:161]
	v_pk_fma_f32 v[46:47], v[46:47], v[154:155], v[162:163]
	v_pk_fma_f32 v[40:41], v[40:41], v[144:145], v[132:133]
	v_pk_fma_f32 v[42:43], v[42:43], v[146:147], v[134:135]
	v_cvt_pk_bf16_f32 v44, v44, v45
	v_cvt_pk_bf16_f32 v45, v46, v47
	v_cvt_pk_bf16_f32 v46, v40, v41
	v_cvt_pk_bf16_f32 v47, v42, v43
	s_add_u32 s64, s12, 0x90000
	s_addc_u32 s65, s13, 0
	global_store_dwordx4 v196, v[44:47], s[64:65]
	s_waitcnt vmcnt(15)
	v_lshlrev_b32_e32 v160, 16, v140
	v_and_b32_e32 v161, 0xffff0000, v140
	v_lshlrev_b32_e32 v162, 16, v141
	v_and_b32_e32 v163, 0xffff0000, v141
	v_lshlrev_b32_e32 v140, 16, v142
	v_and_b32_e32 v141, 0xffff0000, v142
	v_lshlrev_b32_e32 v142, 16, v143
	v_and_b32_e32 v143, 0xffff0000, v143
	v_pk_fma_f32 v[36:37], v[36:37], v[136:137], v[160:161]
	v_pk_fma_f32 v[38:39], v[38:39], v[138:139], v[162:163]
	v_pk_fma_f32 v[32:33], v[32:33], v[128:129], v[140:141]
	v_pk_fma_f32 v[34:35], v[34:35], v[130:131], v[142:143]
	v_cvt_pk_bf16_f32 v36, v36, v37
	v_cvt_pk_bf16_f32 v37, v38, v39
	v_cvt_pk_bf16_f32 v38, v32, v33
	v_cvt_pk_bf16_f32 v39, v34, v35
	s_add_u32 s64, s12, 0x90000
	s_addc_u32 s65, s13, 0
	global_store_dwordx4 v196, v[36:39], s[64:65] offset:256
	s_waitcnt vmcnt(15)
	v_lshlrev_b32_e32 v160, 16, v164
	v_and_b32_e32 v161, 0xffff0000, v164
	v_lshlrev_b32_e32 v162, 16, v165
	v_and_b32_e32 v163, 0xffff0000, v165
	v_lshlrev_b32_e32 v164, 16, v166
	v_and_b32_e32 v165, 0xffff0000, v166
	v_lshlrev_b32_e32 v166, 16, v167
	v_and_b32_e32 v167, 0xffff0000, v167
	v_pk_fma_f32 v[28:29], v[28:29], v[152:153], v[160:161]
	v_pk_fma_f32 v[30:31], v[30:31], v[154:155], v[162:163]
	v_pk_fma_f32 v[24:25], v[24:25], v[144:145], v[164:165]
	v_pk_fma_f32 v[26:27], v[26:27], v[146:147], v[166:167]
	v_cvt_pk_bf16_f32 v28, v28, v29
	v_cvt_pk_bf16_f32 v29, v30, v31
	v_cvt_pk_bf16_f32 v30, v24, v25
	v_cvt_pk_bf16_f32 v31, v26, v27
	s_add_u32 s64, s12, 0xa0000
	s_addc_u32 s65, s13, 0
	global_store_dwordx4 v196, v[28:31], s[64:65]
	s_waitcnt vmcnt(14)
	v_lshlrev_b32_e32 v160, 16, v184
	v_and_b32_e32 v161, 0xffff0000, v184
	v_lshlrev_b32_e32 v162, 16, v185
	v_and_b32_e32 v163, 0xffff0000, v185
	v_lshlrev_b32_e32 v184, 16, v186
	v_and_b32_e32 v185, 0xffff0000, v186
	v_lshlrev_b32_e32 v186, 16, v187
	v_and_b32_e32 v187, 0xffff0000, v187
	v_pk_fma_f32 v[20:21], v[20:21], v[136:137], v[160:161]
	v_pk_fma_f32 v[22:23], v[22:23], v[138:139], v[162:163]
	v_pk_fma_f32 v[16:17], v[16:17], v[128:129], v[184:185]
	v_pk_fma_f32 v[18:19], v[18:19], v[130:131], v[186:187]
	v_cvt_pk_bf16_f32 v20, v20, v21
	v_cvt_pk_bf16_f32 v21, v22, v23
	v_cvt_pk_bf16_f32 v22, v16, v17
	v_cvt_pk_bf16_f32 v23, v18, v19
	s_add_u32 s64, s12, 0xa0000
	s_addc_u32 s65, s13, 0
	global_store_dwordx4 v196, v[20:23], s[64:65] offset:256
	s_waitcnt vmcnt(13)
	v_lshlrev_b32_e32 v160, 16, v188
	v_and_b32_e32 v161, 0xffff0000, v188
	v_lshlrev_b32_e32 v162, 16, v189
	v_and_b32_e32 v163, 0xffff0000, v189
	v_lshlrev_b32_e32 v188, 16, v190
	v_and_b32_e32 v189, 0xffff0000, v190
	v_lshlrev_b32_e32 v190, 16, v191
	v_and_b32_e32 v191, 0xffff0000, v191
	v_pk_fma_f32 v[12:13], v[12:13], v[152:153], v[160:161]
	v_pk_fma_f32 v[14:15], v[14:15], v[154:155], v[162:163]
	v_pk_fma_f32 v[8:9], v[8:9], v[144:145], v[188:189]
	v_pk_fma_f32 v[10:11], v[10:11], v[146:147], v[190:191]
	v_cvt_pk_bf16_f32 v12, v12, v13
	v_cvt_pk_bf16_f32 v13, v14, v15
	v_cvt_pk_bf16_f32 v14, v8, v9
	v_cvt_pk_bf16_f32 v15, v10, v11
	s_add_u32 s64, s12, 0xb0000
	s_addc_u32 s65, s13, 0
	global_store_dwordx4 v196, v[12:15], s[64:65]
	s_waitcnt vmcnt(12)
	v_lshlrev_b32_e32 v160, 16, v208
	v_and_b32_e32 v161, 0xffff0000, v208
	v_lshlrev_b32_e32 v162, 16, v209
	v_and_b32_e32 v163, 0xffff0000, v209
	v_lshlrev_b32_e32 v208, 16, v210
	v_and_b32_e32 v209, 0xffff0000, v210
	v_lshlrev_b32_e32 v210, 16, v211
	v_and_b32_e32 v211, 0xffff0000, v211
	v_pk_fma_f32 v[4:5], v[4:5], v[136:137], v[160:161]
	v_pk_fma_f32 v[6:7], v[6:7], v[138:139], v[162:163]
	v_pk_fma_f32 v[0:1], v[0:1], v[128:129], v[208:209]
	v_pk_fma_f32 v[2:3], v[2:3], v[130:131], v[210:211]
	v_cvt_pk_bf16_f32 v4, v4, v5
	v_cvt_pk_bf16_f32 v5, v6, v7
	v_cvt_pk_bf16_f32 v6, v0, v1
	v_cvt_pk_bf16_f32 v7, v2, v3
	s_add_u32 s64, s12, 0xb0000
	s_addc_u32 s65, s13, 0
	global_store_dwordx4 v196, v[4:7], s[64:65] offset:256
	s_branch .Lres_done

.LBB0_639:
	s_add_i32 s60, s30, 2
	s_add_u32 s29, s26, 0x80
	s_addc_u32 s31, s27, 0
	s_add_i32 s34, 0, 0x10000
	v_add_u32_e32 v156, s34, v141
	ds_read_b128 v[144:147], v156
	ds_read_b128 v[148:151], v156 offset:1024
	ds_read_b128 v[152:155], v156 offset:2048
	ds_read_b128 v[156:159], v156 offset:3072
	s_cmp_eq_u32 s58, s30
	s_cselect_b32 s30, s20, s29
	s_cselect_b32 s31, s21, s31
	s_cselect_b32 s43, s25, s15
	s_cselect_b32 s42, s24, s13
	v_lshl_add_u64 v[196:197], s[26:27], 0, v[136:137]
	s_add_i32 m0, s17, 0xc000
	ds_read_b128 v[160:163], v143
	ds_read_b128 v[164:167], v143 offset:1024
	ds_read_b128 v[168:171], v143 offset:2048
	ds_read_b128 v[172:175], v143 offset:3072
	ds_read_b128 v[180:183], v143 offset:4096
	ds_read_b128 v[184:187], v143 offset:5120
	ds_read_b128 v[188:191], v143 offset:6144
	ds_read_b128 v[192:195], v143 offset:7168
	global_load_lds_dwordx4 v[196:197], off
	v_lshl_add_u64 v[196:197], s[26:27], 0, v[138:139]
	s_add_i32 m0, s17, 0xe000
	s_nop 0
	global_load_lds_dwordx4 v[196:197], off
	s_waitcnt lgkmcnt(0)
	s_barrier
	v_mfma_f32_16x16x32_bf16 v[124:127], v[144:147], v[160:163], v[124:127]
	v_mfma_f32_16x16x32_bf16 v[120:123], v[152:155], v[160:163], v[120:123]
	v_mfma_f32_16x16x32_bf16 v[116:119], v[144:147], v[168:171], v[116:119]
	v_mfma_f32_16x16x32_bf16 v[112:115], v[152:155], v[168:171], v[112:115]
	v_mfma_f32_16x16x32_bf16 v[108:111], v[144:147], v[180:183], v[108:111]
	v_mfma_f32_16x16x32_bf16 v[104:107], v[152:155], v[180:183], v[104:107]
	v_mfma_f32_16x16x32_bf16 v[100:103], v[144:147], v[188:191], v[100:103]
	v_mfma_f32_16x16x32_bf16 v[96:99], v[152:155], v[188:191], v[96:99]
	v_mfma_f32_16x16x32_bf16 v[124:127], v[148:151], v[164:167], v[124:127]
	v_mfma_f32_16x16x32_bf16 v[120:123], v[156:159], v[164:167], v[120:123]
	v_mfma_f32_16x16x32_bf16 v[116:119], v[148:151], v[172:175], v[116:119]
	v_mfma_f32_16x16x32_bf16 v[112:115], v[156:159], v[172:175], v[112:115]
	v_mfma_f32_16x16x32_bf16 v[108:111], v[148:151], v[184:187], v[108:111]
	v_mfma_f32_16x16x32_bf16 v[104:107], v[156:159], v[184:187], v[104:107]
	v_mfma_f32_16x16x32_bf16 v[100:103], v[148:151], v[192:195], v[100:103]
	v_mfma_f32_16x16x32_bf16 v[96:99], v[156:159], v[192:195], v[96:99]
	s_barrier
	s_add_i32 s29, 0, 0x14000
	s_add_i32 s34, s34, s48
	v_add_u32_e32 v176, s29, v141
	v_lshl_add_u64 v[200:201], s[42:43], 0, v[130:131]
	s_mov_b32 m0, s34
	ds_read_b128 v[196:199], v176
	ds_read_b128 v[208:211], v176 offset:1024
	ds_read_b128 v[212:215], v176 offset:2048
	ds_read_b128 v[216:219], v176 offset:3072
	global_load_lds_dwordx4 v[200:201], off
	v_lshl_add_u64 v[220:221], s[42:43], 0, v[134:135]
	s_add_i32 m0, s34, 0x2000
	s_nop 0
	global_load_lds_dwordx4 v[220:221], off
	s_waitcnt lgkmcnt(0)
	s_barrier
	v_mfma_f32_16x16x32_bf16 v[72:75], v[196:199], v[160:163], v[72:75]
	v_mfma_f32_16x16x32_bf16 v[64:67], v[212:215], v[160:163], v[64:67]
	v_mfma_f32_16x16x32_bf16 v[56:59], v[196:199], v[168:171], v[56:59]
	v_mfma_f32_16x16x32_bf16 v[48:51], v[212:215], v[168:171], v[48:51]
	v_mfma_f32_16x16x32_bf16 v[44:47], v[196:199], v[180:183], v[44:47]
	v_mfma_f32_16x16x32_bf16 v[40:43], v[212:215], v[180:183], v[40:43]
	v_mfma_f32_16x16x32_bf16 v[36:39], v[196:199], v[188:191], v[36:39]
	v_mfma_f32_16x16x32_bf16 v[32:35], v[212:215], v[188:191], v[32:35]
	v_mfma_f32_16x16x32_bf16 v[72:75], v[208:211], v[164:167], v[72:75]
	v_mfma_f32_16x16x32_bf16 v[64:67], v[216:219], v[164:167], v[64:67]
	v_mfma_f32_16x16x32_bf16 v[56:59], v[208:211], v[172:175], v[56:59]
	v_mfma_f32_16x16x32_bf16 v[48:51], v[216:219], v[172:175], v[48:51]
	v_mfma_f32_16x16x32_bf16 v[44:47], v[208:211], v[184:187], v[44:47]
	v_mfma_f32_16x16x32_bf16 v[40:43], v[216:219], v[184:187], v[40:43]
	v_mfma_f32_16x16x32_bf16 v[36:39], v[208:211], v[192:195], v[36:39]
	v_mfma_f32_16x16x32_bf16 v[32:35], v[216:219], v[192:195], v[32:35]
	s_mov_b32 m0, s17
	v_lshl_add_u64 v[222:223], s[30:31], 0, v[128:129]
	s_barrier
	ds_read_b128 v[160:163], v143 offset:16384
	ds_read_b128 v[164:167], v143 offset:17408
	ds_read_b128 v[168:171], v143 offset:18432
	ds_read_b128 v[172:175], v143 offset:19456
	ds_read_b128 v[180:183], v143 offset:20480
	ds_read_b128 v[184:187], v143 offset:21504
	ds_read_b128 v[188:191], v143 offset:22528
	ds_read_b128 v[192:195], v143 offset:23552
	global_load_lds_dwordx4 v[222:223], off
	v_lshl_add_u64 v[224:225], s[30:31], 0, v[132:133]
	s_mov_b32 m0, s19
	s_nop 0
	global_load_lds_dwordx4 v[224:225], off
	s_waitcnt lgkmcnt(0)
	s_barrier
	v_mfma_f32_16x16x32_bf16 v[92:95], v[144:147], v[160:163], v[92:95]
	v_mfma_f32_16x16x32_bf16 v[88:91], v[152:155], v[160:163], v[88:91]
	v_mfma_f32_16x16x32_bf16 v[84:87], v[144:147], v[168:171], v[84:87]
	v_mfma_f32_16x16x32_bf16 v[80:83], v[152:155], v[168:171], v[80:83]
	v_mfma_f32_16x16x32_bf16 v[76:79], v[144:147], v[180:183], v[76:79]
	v_mfma_f32_16x16x32_bf16 v[68:71], v[152:155], v[180:183], v[68:71]
	v_mfma_f32_16x16x32_bf16 v[60:63], v[144:147], v[188:191], v[60:63]
	v_mfma_f32_16x16x32_bf16 v[52:55], v[152:155], v[188:191], v[52:55]
	v_mfma_f32_16x16x32_bf16 v[92:95], v[148:151], v[164:167], v[92:95]
	v_mfma_f32_16x16x32_bf16 v[88:91], v[156:159], v[164:167], v[88:91]
	v_mfma_f32_16x16x32_bf16 v[84:87], v[148:151], v[172:175], v[84:87]
	v_mfma_f32_16x16x32_bf16 v[80:83], v[156:159], v[172:175], v[80:83]
	v_mfma_f32_16x16x32_bf16 v[76:79], v[148:151], v[184:187], v[76:79]
	v_mfma_f32_16x16x32_bf16 v[68:71], v[156:159], v[184:187], v[68:71]
	v_mfma_f32_16x16x32_bf16 v[60:63], v[148:151], v[192:195], v[60:63]
	v_mfma_f32_16x16x32_bf16 v[52:55], v[156:159], v[192:195], v[52:55]
	s_barrier
	s_add_u32 s34, s42, s44
	s_addc_u32 s35, s43, 0
	s_add_i32 s29, s29, s48
	v_lshl_add_u64 v[226:227], s[34:35], 0, v[130:131]
	s_mov_b32 m0, s29
	v_lshl_add_u64 v[228:229], s[34:35], 0, v[134:135]
	global_load_lds_dwordx4 v[226:227], off
	s_add_i32 m0, s29, 0x2000
	s_nop 0
	global_load_lds_dwordx4 v[228:229], off
	s_waitcnt vmcnt(6)
	s_barrier
	v_mfma_f32_16x16x32_bf16 v[28:31], v[196:199], v[160:163], v[28:31]
	v_mfma_f32_16x16x32_bf16 v[24:27], v[212:215], v[160:163], v[24:27]
	v_mfma_f32_16x16x32_bf16 v[20:23], v[196:199], v[168:171], v[20:23]
	v_mfma_f32_16x16x32_bf16 v[16:19], v[212:215], v[168:171], v[16:19]
	v_mfma_f32_16x16x32_bf16 v[12:15], v[196:199], v[180:183], v[12:15]
	v_mfma_f32_16x16x32_bf16 v[8:11], v[212:215], v[180:183], v[8:11]
	v_mfma_f32_16x16x32_bf16 v[4:7], v[196:199], v[188:191], v[4:7]
	v_mfma_f32_16x16x32_bf16 v[0:3], v[212:215], v[188:191], v[0:3]
	v_mfma_f32_16x16x32_bf16 v[28:31], v[208:211], v[164:167], v[28:31]
	v_mfma_f32_16x16x32_bf16 v[24:27], v[216:219], v[164:167], v[24:27]
	v_mfma_f32_16x16x32_bf16 v[20:23], v[208:211], v[172:175], v[20:23]
	v_mfma_f32_16x16x32_bf16 v[16:19], v[216:219], v[172:175], v[16:19]
	v_mfma_f32_16x16x32_bf16 v[12:15], v[208:211], v[184:187], v[12:15]
	v_mfma_f32_16x16x32_bf16 v[8:11], v[216:219], v[184:187], v[8:11]
	v_mfma_f32_16x16x32_bf16 v[4:7], v[208:211], v[192:195], v[4:7]
	v_mfma_f32_16x16x32_bf16 v[0:3], v[216:219], v[192:195], v[0:3]
	s_add_i32 s29, 0, 0x18000
	v_add_u32_e32 v156, s29, v141
	s_barrier
	ds_read_b128 v[144:147], v156
	ds_read_b128 v[148:151], v156 offset:1024
	ds_read_b128 v[152:155], v156 offset:2048
	ds_read_b128 v[156:159], v156 offset:3072
	s_add_u32 s30, s30, s44
	s_addc_u32 s31, s31, 0
	s_mov_b32 m0, s51
	v_lshl_add_u64 v[196:197], s[30:31], 0, v[128:129]
	ds_read_b128 v[160:163], v143 offset:32768
	ds_read_b128 v[164:167], v143 offset:33792
	ds_read_b128 v[168:171], v143 offset:34816
	ds_read_b128 v[172:175], v143 offset:35840
	ds_read_b128 v[180:183], v143 offset:36864
	ds_read_b128 v[184:187], v143 offset:37888
	ds_read_b128 v[188:191], v143 offset:38912
	ds_read_b128 v[192:195], v143 offset:39936
	global_load_lds_dwordx4 v[196:197], off
	v_lshl_add_u64 v[196:197], s[30:31], 0, v[132:133]
	s_mov_b32 m0, s52
	s_nop 0
	global_load_lds_dwordx4 v[196:197], off
	s_waitcnt lgkmcnt(0)
	s_barrier
	v_mfma_f32_16x16x32_bf16 v[124:127], v[144:147], v[160:163], v[124:127]
	v_mfma_f32_16x16x32_bf16 v[120:123], v[152:155], v[160:163], v[120:123]
	v_mfma_f32_16x16x32_bf16 v[116:119], v[144:147], v[168:171], v[116:119]
	v_mfma_f32_16x16x32_bf16 v[112:115], v[152:155], v[168:171], v[112:115]
	v_mfma_f32_16x16x32_bf16 v[108:111], v[144:147], v[180:183], v[108:111]
	v_mfma_f32_16x16x32_bf16 v[104:107], v[152:155], v[180:183], v[104:107]
	v_mfma_f32_16x16x32_bf16 v[100:103], v[144:147], v[188:191], v[100:103]
	v_mfma_f32_16x16x32_bf16 v[96:99], v[152:155], v[188:191], v[96:99]
	v_mfma_f32_16x16x32_bf16 v[124:127], v[148:151], v[164:167], v[124:127]
	v_mfma_f32_16x16x32_bf16 v[120:123], v[156:159], v[164:167], v[120:123]
	v_mfma_f32_16x16x32_bf16 v[116:119], v[148:151], v[172:175], v[116:119]
	v_mfma_f32_16x16x32_bf16 v[112:115], v[156:159], v[172:175], v[112:115]
	v_mfma_f32_16x16x32_bf16 v[108:111], v[148:151], v[184:187], v[108:111]
	v_mfma_f32_16x16x32_bf16 v[104:107], v[156:159], v[184:187], v[104:107]
	v_mfma_f32_16x16x32_bf16 v[100:103], v[148:151], v[192:195], v[100:103]
	v_mfma_f32_16x16x32_bf16 v[96:99], v[156:159], v[192:195], v[96:99]
	s_barrier
	s_add_i32 s30, 0, 0x1c000
	s_add_i32 s29, s29, s48
	v_add_u32_e32 v176, s30, v141
	v_lshl_add_u64 v[200:201], v[200:201], 0, s[40:41]
	s_mov_b32 m0, s29
	ds_read_b128 v[196:199], v176
	ds_read_b128 v[208:211], v176 offset:1024
	ds_read_b128 v[212:215], v176 offset:2048
	ds_read_b128 v[216:219], v176 offset:3072
	global_load_lds_dwordx4 v[200:201], off
	v_lshl_add_u64 v[200:201], v[220:221], 0, s[40:41]
	s_add_i32 m0, s29, 0x2000
	s_nop 0
	global_load_lds_dwordx4 v[200:201], off
	s_waitcnt lgkmcnt(0)
	s_barrier
	v_mfma_f32_16x16x32_bf16 v[72:75], v[196:199], v[160:163], v[72:75]
	v_mfma_f32_16x16x32_bf16 v[64:67], v[212:215], v[160:163], v[64:67]
	v_mfma_f32_16x16x32_bf16 v[56:59], v[196:199], v[168:171], v[56:59]
	v_mfma_f32_16x16x32_bf16 v[48:51], v[212:215], v[168:171], v[48:51]
	v_mfma_f32_16x16x32_bf16 v[44:47], v[196:199], v[180:183], v[44:47]
	v_mfma_f32_16x16x32_bf16 v[40:43], v[212:215], v[180:183], v[40:43]
	v_mfma_f32_16x16x32_bf16 v[36:39], v[196:199], v[188:191], v[36:39]
	v_mfma_f32_16x16x32_bf16 v[32:35], v[212:215], v[188:191], v[32:35]
	v_mfma_f32_16x16x32_bf16 v[72:75], v[208:211], v[164:167], v[72:75]
	v_mfma_f32_16x16x32_bf16 v[64:67], v[216:219], v[164:167], v[64:67]
	v_mfma_f32_16x16x32_bf16 v[56:59], v[208:211], v[172:175], v[56:59]
	v_mfma_f32_16x16x32_bf16 v[48:51], v[216:219], v[172:175], v[48:51]
	v_mfma_f32_16x16x32_bf16 v[44:47], v[208:211], v[184:187], v[44:47]
	v_mfma_f32_16x16x32_bf16 v[40:43], v[216:219], v[184:187], v[40:43]
	v_mfma_f32_16x16x32_bf16 v[36:39], v[208:211], v[192:195], v[36:39]
	v_mfma_f32_16x16x32_bf16 v[32:35], v[216:219], v[192:195], v[32:35]
	s_mov_b32 m0, s56
	v_lshl_add_u64 v[200:201], v[222:223], 0, s[40:41]
	s_barrier
	ds_read_b128 v[160:163], v143 offset:49152
	ds_read_b128 v[164:167], v143 offset:50176
	ds_read_b128 v[168:171], v143 offset:51200
	ds_read_b128 v[172:175], v143 offset:52224
	ds_read_b128 v[180:183], v143 offset:53248
	ds_read_b128 v[184:187], v143 offset:54272
	ds_read_b128 v[188:191], v143 offset:55296
	ds_read_b128 v[192:195], v143 offset:56320
	global_load_lds_dwordx4 v[200:201], off
	v_lshl_add_u64 v[200:201], v[224:225], 0, s[40:41]
	s_mov_b32 m0, s57
	s_nop 0
	global_load_lds_dwordx4 v[200:201], off
	s_waitcnt lgkmcnt(0)
	s_barrier
	v_mfma_f32_16x16x32_bf16 v[92:95], v[144:147], v[160:163], v[92:95]
	v_mfma_f32_16x16x32_bf16 v[88:91], v[152:155], v[160:163], v[88:91]
	v_mfma_f32_16x16x32_bf16 v[84:87], v[144:147], v[168:171], v[84:87]
	v_mfma_f32_16x16x32_bf16 v[80:83], v[152:155], v[168:171], v[80:83]
	v_mfma_f32_16x16x32_bf16 v[76:79], v[144:147], v[180:183], v[76:79]
	v_mfma_f32_16x16x32_bf16 v[68:71], v[152:155], v[180:183], v[68:71]
	v_mfma_f32_16x16x32_bf16 v[60:63], v[144:147], v[188:191], v[60:63]
	v_mfma_f32_16x16x32_bf16 v[52:55], v[152:155], v[188:191], v[52:55]
	v_mfma_f32_16x16x32_bf16 v[92:95], v[148:151], v[164:167], v[92:95]
	v_mfma_f32_16x16x32_bf16 v[88:91], v[156:159], v[164:167], v[88:91]
	v_mfma_f32_16x16x32_bf16 v[84:87], v[148:151], v[172:175], v[84:87]
	v_mfma_f32_16x16x32_bf16 v[80:83], v[156:159], v[172:175], v[80:83]
	v_mfma_f32_16x16x32_bf16 v[76:79], v[148:151], v[184:187], v[76:79]
	v_mfma_f32_16x16x32_bf16 v[68:71], v[156:159], v[184:187], v[68:71]
	v_mfma_f32_16x16x32_bf16 v[60:63], v[148:151], v[192:195], v[60:63]
	v_mfma_f32_16x16x32_bf16 v[52:55], v[156:159], v[192:195], v[52:55]
	s_barrier
	s_add_i32 s29, s30, s48
	v_lshl_add_u64 v[144:145], v[226:227], 0, s[40:41]
	s_mov_b32 m0, s29
	s_nop 0
	global_load_lds_dwordx4 v[144:145], off
	v_lshl_add_u64 v[144:145], v[228:229], 0, s[40:41]
	s_add_i32 m0, s29, 0x2000
	s_nop 0
	global_load_lds_dwordx4 v[144:145], off
	s_waitcnt vmcnt(6)
	s_barrier
	v_mfma_f32_16x16x32_bf16 v[28:31], v[196:199], v[160:163], v[28:31]
	v_mfma_f32_16x16x32_bf16 v[24:27], v[212:215], v[160:163], v[24:27]
	v_mfma_f32_16x16x32_bf16 v[20:23], v[196:199], v[168:171], v[20:23]
	v_mfma_f32_16x16x32_bf16 v[16:19], v[212:215], v[168:171], v[16:19]
	v_mfma_f32_16x16x32_bf16 v[12:15], v[196:199], v[180:183], v[12:15]
	v_mfma_f32_16x16x32_bf16 v[8:11], v[212:215], v[180:183], v[8:11]
	v_mfma_f32_16x16x32_bf16 v[4:7], v[196:199], v[188:191], v[4:7]
	v_mfma_f32_16x16x32_bf16 v[0:3], v[212:215], v[188:191], v[0:3]
	v_mfma_f32_16x16x32_bf16 v[28:31], v[208:211], v[164:167], v[28:31]
	v_mfma_f32_16x16x32_bf16 v[24:27], v[216:219], v[164:167], v[24:27]
	v_mfma_f32_16x16x32_bf16 v[20:23], v[208:211], v[172:175], v[20:23]
	v_mfma_f32_16x16x32_bf16 v[16:19], v[216:219], v[172:175], v[16:19]
	v_mfma_f32_16x16x32_bf16 v[12:15], v[208:211], v[184:187], v[12:15]
	v_mfma_f32_16x16x32_bf16 v[8:11], v[216:219], v[184:187], v[8:11]
	v_mfma_f32_16x16x32_bf16 v[4:7], v[208:211], v[192:195], v[4:7]
	v_mfma_f32_16x16x32_bf16 v[0:3], v[216:219], v[192:195], v[0:3]
	s_add_u32 s26, s26, 0x100
	s_addc_u32 s27, s27, 0
	s_add_u32 s13, s13, 0x100
	s_addc_u32 s15, s15, 0
	s_cmp_ge_u32 s60, s55
	s_mov_b32 s30, s60
	s_barrier
	s_cbranch_scc0 .LBB0_639
	s_lshl_b32 s13, s16, 8
	s_ashr_i32 s15, s16, 1
	s_and_b32 s13, s13, 0x100
	v_or_b32_e32 v145, s13, v142
	s_lshl_b32 s13, s15, s59
	s_add_i32 s26, s13, s54
	s_ashr_i32 s27, s26, 31
	s_lshl_b64 s[26:27], s[26:27], 12
	v_readlane_b32 s30, v255, 26
	v_lshl_add_u32 v144, s18, 8, v140
	v_readlane_b32 s31, v255, 27
	s_add_u32 s26, s30, s26
	s_addc_u32 s27, s31, s27
	v_lshlrev_b32_e32 v176, 1, v145
	v_pk_mul_f32 v[124:125], s[8:9], v[124:125]
	v_ashrrev_i32_e32 v145, 31, v144
	v_lshl_add_u64 v[146:147], s[26:27], 0, v[176:177]
	v_pk_mul_f32 v[148:149], s[10:11], v[122:123]
	v_pk_mul_f32 v[122:123], s[8:9], v[120:121]
	v_cvt_pk_bf16_f32 v120, v124, v125
	v_lshlrev_b64 v[124:125], 12, v[144:145]
	v_pk_mul_f32 v[126:127], s[10:11], v[126:127]
	v_lshl_add_u64 v[124:125], v[146:147], 0, v[124:125]
	v_cvt_pk_bf16_f32 v121, v126, v127
	v_pk_mul_f32 v[116:117], s[8:9], v[116:117]
	v_cvt_pk_bf16_f32 v122, v122, v123
	v_cvt_pk_bf16_f32 v123, v148, v149
	global_store_dwordx4 v[124:125], v[120:123], off offset:3072
	v_pk_mul_f32 v[118:119], s[10:11], v[118:119]
	v_pk_mul_f32 v[108:109], s[8:9], v[108:109]
	v_pk_mul_f32 v[120:121], s[10:11], v[114:115]
	v_pk_mul_f32 v[114:115], s[8:9], v[112:113]
	v_cvt_pk_bf16_f32 v112, v116, v117
	v_or_b32_e32 v116, 16, v144
	v_ashrrev_i32_e32 v117, 31, v116
	v_lshlrev_b64 v[116:117], 12, v[116:117]
	v_cvt_pk_bf16_f32 v113, v118, v119
	v_lshl_add_u64 v[116:117], v[146:147], 0, v[116:117]
	v_cvt_pk_bf16_f32 v114, v114, v115
	v_cvt_pk_bf16_f32 v115, v120, v121
	global_store_dwordx4 v[116:117], v[112:115], off offset:3072
	v_pk_mul_f32 v[110:111], s[10:11], v[110:111]
	v_pk_mul_f32 v[100:101], s[8:9], v[100:101]
	v_pk_mul_f32 v[112:113], s[10:11], v[106:107]
	v_pk_mul_f32 v[106:107], s[8:9], v[104:105]
	v_cvt_pk_bf16_f32 v104, v108, v109
	v_or_b32_e32 v108, 32, v144
	v_ashrrev_i32_e32 v109, 31, v108
	v_lshlrev_b64 v[108:109], 12, v[108:109]
	v_cvt_pk_bf16_f32 v105, v110, v111
	v_lshl_add_u64 v[108:109], v[146:147], 0, v[108:109]
	v_cvt_pk_bf16_f32 v106, v106, v107
	v_cvt_pk_bf16_f32 v107, v112, v113
	global_store_dwordx4 v[108:109], v[104:107], off offset:3072
	v_pk_mul_f32 v[102:103], s[10:11], v[102:103]
	v_pk_mul_f32 v[92:93], s[8:9], v[92:93]
	v_pk_mul_f32 v[104:105], s[10:11], v[98:99]
	v_pk_mul_f32 v[98:99], s[8:9], v[96:97]
	v_cvt_pk_bf16_f32 v96, v100, v101
	v_or_b32_e32 v100, 48, v144
	v_ashrrev_i32_e32 v101, 31, v100
	v_lshlrev_b64 v[100:101], 12, v[100:101]
	v_cvt_pk_bf16_f32 v97, v102, v103
	v_lshl_add_u64 v[100:101], v[146:147], 0, v[100:101]
	s_mov_b64 s[26:27], 0x80000
	v_cvt_pk_bf16_f32 v98, v98, v99
	v_cvt_pk_bf16_f32 v99, v104, v105
	global_store_dwordx4 v[100:101], v[96:99], off offset:3072
	v_pk_mul_f32 v[94:95], s[10:11], v[94:95]
	v_pk_mul_f32 v[84:85], s[8:9], v[84:85]
	v_pk_mul_f32 v[96:97], s[10:11], v[90:91]
	v_pk_mul_f32 v[90:91], s[8:9], v[88:89]
	v_cvt_pk_bf16_f32 v88, v92, v93
	v_cvt_pk_bf16_f32 v89, v94, v95
	v_lshl_add_u64 v[92:93], v[124:125], 0, s[26:27]
	s_mov_b64 s[26:27], 0x90000
	v_cvt_pk_bf16_f32 v90, v90, v91
	v_cvt_pk_bf16_f32 v91, v96, v97
	global_store_dwordx4 v[92:93], v[88:91], off offset:3072
	v_pk_mul_f32 v[86:87], s[10:11], v[86:87]
	v_pk_mul_f32 v[76:77], s[8:9], v[76:77]
	v_pk_mul_f32 v[88:89], s[10:11], v[82:83]
	v_pk_mul_f32 v[82:83], s[8:9], v[80:81]
	v_cvt_pk_bf16_f32 v80, v84, v85
	v_cvt_pk_bf16_f32 v81, v86, v87
	v_lshl_add_u64 v[84:85], v[124:125], 0, s[26:27]
	s_mov_b64 s[26:27], 0xa0000
	v_cvt_pk_bf16_f32 v82, v82, v83
	v_cvt_pk_bf16_f32 v83, v88, v89
	global_store_dwordx4 v[84:85], v[80:83], off offset:3072
	v_pk_mul_f32 v[78:79], s[10:11], v[78:79]
	v_pk_mul_f32 v[60:61], s[8:9], v[60:61]
	v_pk_mul_f32 v[80:81], s[10:11], v[70:71]
	v_pk_mul_f32 v[70:71], s[8:9], v[68:69]
	v_cvt_pk_bf16_f32 v68, v76, v77
	v_cvt_pk_bf16_f32 v69, v78, v79
	v_lshl_add_u64 v[76:77], v[124:125], 0, s[26:27]
	v_cvt_pk_bf16_f32 v70, v70, v71
	v_cvt_pk_bf16_f32 v71, v80, v81
	global_store_dwordx4 v[76:77], v[68:71], off offset:3072
	s_mov_b64 s[26:27], 0xb0000
	v_pk_mul_f32 v[62:63], s[10:11], v[62:63]
	v_pk_mul_f32 v[68:69], s[10:11], v[54:55]
	v_pk_mul_f32 v[54:55], s[8:9], v[52:53]
	v_cvt_pk_bf16_f32 v52, v60, v61
	v_cvt_pk_bf16_f32 v53, v62, v63
	v_lshl_add_u64 v[60:61], v[124:125], 0, s[26:27]
	v_cvt_pk_bf16_f32 v54, v54, v55
	v_cvt_pk_bf16_f32 v55, v68, v69
	global_store_dwordx4 v[60:61], v[52:55], off offset:3072
	v_pk_mul_f32 v[62:63], s[10:11], v[66:67]
	v_pk_mul_f32 v[64:65], s[8:9], v[64:65]
	v_pk_mul_f32 v[54:55], s[10:11], v[74:75]
	v_pk_mul_f32 v[52:53], s[8:9], v[72:73]
	v_pk_mul_f32 v[46:47], s[10:11], v[46:47]
	v_cvt_pk_bf16_f32 v52, v52, v53
	v_cvt_pk_bf16_f32 v53, v54, v55
	v_cvt_pk_bf16_f32 v54, v64, v65
	v_cvt_pk_bf16_f32 v55, v62, v63
	global_store_dwordx4 v[124:125], v[52:55], off offset:3328
	v_pk_mul_f32 v[44:45], s[8:9], v[44:45]
	v_pk_mul_f32 v[38:39], s[10:11], v[38:39]
	v_pk_mul_f32 v[52:53], s[10:11], v[58:59]
	v_pk_mul_f32 v[54:55], s[8:9], v[56:57]
	v_pk_mul_f32 v[56:57], s[10:11], v[50:51]
	v_pk_mul_f32 v[50:51], s[8:9], v[48:49]
	v_cvt_pk_bf16_f32 v48, v54, v55
	v_cvt_pk_bf16_f32 v49, v52, v53
	v_pk_mul_f32 v[36:37], s[8:9], v[36:37]
	v_cvt_pk_bf16_f32 v50, v50, v51
	v_cvt_pk_bf16_f32 v51, v56, v57
	global_store_dwordx4 v[116:117], v[48:51], off offset:3328
	v_pk_mul_f32 v[30:31], s[10:11], v[30:31]
	v_pk_mul_f32 v[28:29], s[8:9], v[28:29]
	v_pk_mul_f32 v[48:49], s[10:11], v[42:43]
	v_pk_mul_f32 v[42:43], s[8:9], v[40:41]
	v_cvt_pk_bf16_f32 v40, v44, v45
	v_cvt_pk_bf16_f32 v41, v46, v47
	v_pk_mul_f32 v[22:23], s[10:11], v[22:23]
	v_cvt_pk_bf16_f32 v42, v42, v43
	v_cvt_pk_bf16_f32 v43, v48, v49
	global_store_dwordx4 v[108:109], v[40:43], off offset:3328
	v_pk_mul_f32 v[20:21], s[8:9], v[20:21]
	v_pk_mul_f32 v[14:15], s[10:11], v[14:15]
	v_pk_mul_f32 v[40:41], s[10:11], v[34:35]
	v_pk_mul_f32 v[34:35], s[8:9], v[32:33]
	v_cvt_pk_bf16_f32 v32, v36, v37
	v_cvt_pk_bf16_f32 v33, v38, v39
	v_pk_mul_f32 v[12:13], s[8:9], v[12:13]
	v_cvt_pk_bf16_f32 v34, v34, v35
	v_cvt_pk_bf16_f32 v35, v40, v41
	global_store_dwordx4 v[100:101], v[32:35], off offset:3328
	s_and_b64 vcc, exec, s[6:7]
	s_mov_b32 s16, s12
	v_pk_mul_f32 v[32:33], s[10:11], v[26:27]
	v_pk_mul_f32 v[26:27], s[8:9], v[24:25]
	v_cvt_pk_bf16_f32 v24, v28, v29
	v_cvt_pk_bf16_f32 v25, v30, v31
	s_mov_b32 s18, s14
	v_cvt_pk_bf16_f32 v26, v26, v27
	v_cvt_pk_bf16_f32 v27, v32, v33
	global_store_dwordx4 v[92:93], v[24:27], off offset:3328
	s_mov_b64 s[30:31], s[24:25]
	s_mov_b64 s[26:27], s[20:21]
	v_pk_mul_f32 v[24:25], s[10:11], v[18:19]
	v_pk_mul_f32 v[18:19], s[8:9], v[16:17]
	v_cvt_pk_bf16_f32 v16, v20, v21
	v_cvt_pk_bf16_f32 v17, v22, v23
	v_pk_mul_f32 v[6:7], s[10:11], v[6:7]
	v_cvt_pk_bf16_f32 v18, v18, v19
	v_cvt_pk_bf16_f32 v19, v24, v25
	global_store_dwordx4 v[84:85], v[16:19], off offset:3328
	v_pk_mul_f32 v[4:5], s[8:9], v[4:5]
	s_nop 0
	v_pk_mul_f32 v[16:17], s[10:11], v[10:11]
	v_pk_mul_f32 v[10:11], s[8:9], v[8:9]
	v_cvt_pk_bf16_f32 v8, v12, v13
	v_cvt_pk_bf16_f32 v9, v14, v15
	s_nop 0
	v_cvt_pk_bf16_f32 v10, v10, v11
	v_cvt_pk_bf16_f32 v11, v16, v17
	global_store_dwordx4 v[76:77], v[8:11], off offset:3328
	s_nop 1
	v_pk_mul_f32 v[8:9], s[10:11], v[2:3]
	v_pk_mul_f32 v[2:3], s[8:9], v[0:1]
	v_cvt_pk_bf16_f32 v0, v4, v5
	v_cvt_pk_bf16_f32 v1, v6, v7
	s_nop 0
	v_cvt_pk_bf16_f32 v2, v2, v3
	v_cvt_pk_bf16_f32 v3, v8, v9
	global_store_dwordx4 v[60:61], v[0:3], off offset:3328
	s_cbranch_vccz .LBB0_636
	s_waitcnt vmcnt(0)
	s_setprio 0
	s_cmpk_gt_u32 s1, 0xff
	s_cbranch_scc1 .LBB0_626
	s_barrier
	s_branch .LBB0_626

.LBB0_656:
	s_add_u32 s20, s18, 0xfff80080
	s_addc_u32 s21, s19, -1
	s_add_i32 s34, 0, 0x10000
	v_add_u32_e32 v152, s34, v174
	ds_read_b128 v[140:143], v152
	ds_read_b128 v[144:147], v152 offset:1024
	ds_read_b128 v[148:151], v152 offset:2048
	ds_read_b128 v[152:155], v152 offset:3072
	s_cmp_eq_u32 s54, 28
	s_cselect_b32 s25, s9, s21
	s_cselect_b32 s24, s15, s20
	s_cselect_b32 s21, s5, s53
	s_cselect_b32 s20, s17, s44
	v_lshl_add_u64 v[180:181], s[18:19], 0, v[136:137]
	s_add_i32 m0, s30, 0xc000
	ds_read_b128 v[156:159], v189
	ds_read_b128 v[160:163], v189 offset:1024
	ds_read_b128 v[164:167], v189 offset:2048
	ds_read_b128 v[168:171], v189 offset:3072
	ds_read_b128 v[190:193], v189 offset:4096
	ds_read_b128 v[194:197], v189 offset:5120
	ds_read_b128 v[198:201], v189 offset:6144
	ds_read_b128 v[208:211], v189 offset:7168
	global_load_lds_dwordx4 v[180:181], off
	v_lshl_add_u64 v[180:181], s[18:19], 0, v[138:139]
	s_add_i32 m0, s30, 0xe000
	s_nop 0
	global_load_lds_dwordx4 v[180:181], off
	s_waitcnt lgkmcnt(0)
	s_barrier
	v_mfma_f32_16x16x32_bf16 v[124:127], v[140:143], v[156:159], v[124:127]
	v_mfma_f32_16x16x32_bf16 v[120:123], v[148:151], v[156:159], v[120:123]
	v_mfma_f32_16x16x32_bf16 v[108:111], v[140:143], v[164:167], v[108:111]
	v_mfma_f32_16x16x32_bf16 v[104:107], v[148:151], v[164:167], v[104:107]
	v_mfma_f32_16x16x32_bf16 v[92:95], v[140:143], v[190:193], v[92:95]
	v_mfma_f32_16x16x32_bf16 v[88:91], v[148:151], v[190:193], v[88:91]
	v_mfma_f32_16x16x32_bf16 v[76:79], v[140:143], v[198:201], v[76:79]
	v_mfma_f32_16x16x32_bf16 v[72:75], v[148:151], v[198:201], v[72:75]
	v_mfma_f32_16x16x32_bf16 v[124:127], v[144:147], v[160:163], v[124:127]
	v_mfma_f32_16x16x32_bf16 v[120:123], v[152:155], v[160:163], v[120:123]
	v_mfma_f32_16x16x32_bf16 v[108:111], v[144:147], v[168:171], v[108:111]
	v_mfma_f32_16x16x32_bf16 v[104:107], v[152:155], v[168:171], v[104:107]
	v_mfma_f32_16x16x32_bf16 v[92:95], v[144:147], v[194:197], v[92:95]
	v_mfma_f32_16x16x32_bf16 v[88:91], v[152:155], v[194:197], v[88:91]
	v_mfma_f32_16x16x32_bf16 v[76:79], v[144:147], v[208:211], v[76:79]
	v_mfma_f32_16x16x32_bf16 v[72:75], v[152:155], v[208:211], v[72:75]
	s_barrier
	s_add_i32 s35, 0, 0x14000
	s_add_i32 s34, s34, s28
	v_add_u32_e32 v176, s35, v174
	v_lshl_add_u64 v[180:181], s[20:21], 0, v[130:131]
	s_mov_b32 m0, s34
	ds_read_b128 v[212:215], v176
	ds_read_b128 v[216:219], v176 offset:1024
	ds_read_b128 v[220:223], v176 offset:2048
	ds_read_b128 v[224:227], v176 offset:3072
	global_load_lds_dwordx4 v[180:181], off
	v_lshl_add_u64 v[228:229], s[20:21], 0, v[134:135]
	s_add_i32 m0, s34, 0x2000
	s_nop 0
	global_load_lds_dwordx4 v[228:229], off
	s_waitcnt lgkmcnt(0)
	s_barrier
	v_mfma_f32_16x16x32_bf16 v[116:119], v[212:215], v[156:159], v[116:119]
	v_mfma_f32_16x16x32_bf16 v[112:115], v[220:223], v[156:159], v[112:115]
	v_mfma_f32_16x16x32_bf16 v[100:103], v[212:215], v[164:167], v[100:103]
	v_mfma_f32_16x16x32_bf16 v[96:99], v[220:223], v[164:167], v[96:99]
	v_mfma_f32_16x16x32_bf16 v[84:87], v[212:215], v[190:193], v[84:87]
	v_mfma_f32_16x16x32_bf16 v[80:83], v[220:223], v[190:193], v[80:83]
	v_mfma_f32_16x16x32_bf16 v[68:71], v[212:215], v[198:201], v[68:71]
	v_mfma_f32_16x16x32_bf16 v[64:67], v[220:223], v[198:201], v[64:67]
	v_mfma_f32_16x16x32_bf16 v[116:119], v[216:219], v[160:163], v[116:119]
	v_mfma_f32_16x16x32_bf16 v[112:115], v[224:227], v[160:163], v[112:115]
	v_mfma_f32_16x16x32_bf16 v[100:103], v[216:219], v[168:171], v[100:103]
	v_mfma_f32_16x16x32_bf16 v[96:99], v[224:227], v[168:171], v[96:99]
	v_mfma_f32_16x16x32_bf16 v[84:87], v[216:219], v[194:197], v[84:87]
	v_mfma_f32_16x16x32_bf16 v[80:83], v[224:227], v[194:197], v[80:83]
	v_mfma_f32_16x16x32_bf16 v[68:71], v[216:219], v[208:211], v[68:71]
	v_mfma_f32_16x16x32_bf16 v[64:67], v[224:227], v[208:211], v[64:67]
	s_mov_b32 m0, s30
	v_lshl_add_u64 v[230:231], s[24:25], 0, v[128:129]
	s_barrier
	ds_read_b128 v[156:159], v189 offset:16384
	ds_read_b128 v[160:163], v189 offset:17408
	ds_read_b128 v[164:167], v189 offset:18432
	ds_read_b128 v[168:171], v189 offset:19456
	ds_read_b128 v[190:193], v189 offset:20480
	ds_read_b128 v[194:197], v189 offset:21504
	ds_read_b128 v[198:201], v189 offset:22528
	ds_read_b128 v[208:211], v189 offset:23552
	global_load_lds_dwordx4 v[230:231], off
	v_lshl_add_u64 v[232:233], s[24:25], 0, v[132:133]
	s_mov_b32 m0, s31
	s_nop 0
	global_load_lds_dwordx4 v[232:233], off
	s_waitcnt lgkmcnt(0)
	s_barrier
	v_mfma_f32_16x16x32_bf16 v[60:63], v[140:143], v[156:159], v[60:63]
	v_mfma_f32_16x16x32_bf16 v[56:59], v[148:151], v[156:159], v[56:59]
	v_mfma_f32_16x16x32_bf16 v[44:47], v[140:143], v[164:167], v[44:47]
	v_mfma_f32_16x16x32_bf16 v[40:43], v[148:151], v[164:167], v[40:43]
	v_mfma_f32_16x16x32_bf16 v[28:31], v[140:143], v[190:193], v[28:31]
	v_mfma_f32_16x16x32_bf16 v[24:27], v[148:151], v[190:193], v[24:27]
	v_mfma_f32_16x16x32_bf16 v[12:15], v[140:143], v[198:201], v[12:15]
	v_mfma_f32_16x16x32_bf16 v[8:11], v[148:151], v[198:201], v[8:11]
	v_mfma_f32_16x16x32_bf16 v[60:63], v[144:147], v[160:163], v[60:63]
	v_mfma_f32_16x16x32_bf16 v[56:59], v[152:155], v[160:163], v[56:59]
	v_mfma_f32_16x16x32_bf16 v[44:47], v[144:147], v[168:171], v[44:47]
	v_mfma_f32_16x16x32_bf16 v[40:43], v[152:155], v[168:171], v[40:43]
	v_mfma_f32_16x16x32_bf16 v[28:31], v[144:147], v[194:197], v[28:31]
	v_mfma_f32_16x16x32_bf16 v[24:27], v[152:155], v[194:197], v[24:27]
	v_mfma_f32_16x16x32_bf16 v[12:15], v[144:147], v[208:211], v[12:15]
	v_mfma_f32_16x16x32_bf16 v[8:11], v[152:155], v[208:211], v[8:11]
	s_barrier
	s_add_u32 s56, s20, 0x80000
	s_addc_u32 s57, s21, 0
	s_add_i32 s34, s35, s28
	v_lshl_add_u64 v[140:141], s[56:57], 0, v[130:131]
	s_mov_b32 m0, s34
	s_nop 0
	global_load_lds_dwordx4 v[140:141], off
	v_lshl_add_u64 v[140:141], s[56:57], 0, v[134:135]
	s_add_i32 m0, s34, 0x2000
	s_nop 0
	global_load_lds_dwordx4 v[140:141], off
	s_waitcnt vmcnt(6)
	s_barrier
	v_mfma_f32_16x16x32_bf16 v[52:55], v[212:215], v[156:159], v[52:55]
	v_mfma_f32_16x16x32_bf16 v[48:51], v[220:223], v[156:159], v[48:51]
	v_mfma_f32_16x16x32_bf16 v[36:39], v[212:215], v[164:167], v[36:39]
	v_mfma_f32_16x16x32_bf16 v[32:35], v[220:223], v[164:167], v[32:35]
	v_mfma_f32_16x16x32_bf16 v[20:23], v[212:215], v[190:193], v[20:23]
	v_mfma_f32_16x16x32_bf16 v[16:19], v[220:223], v[190:193], v[16:19]
	v_mfma_f32_16x16x32_bf16 v[4:7], v[212:215], v[198:201], v[4:7]
	v_mfma_f32_16x16x32_bf16 v[0:3], v[220:223], v[198:201], v[0:3]
	v_mfma_f32_16x16x32_bf16 v[52:55], v[216:219], v[160:163], v[52:55]
	v_mfma_f32_16x16x32_bf16 v[48:51], v[224:227], v[160:163], v[48:51]
	v_mfma_f32_16x16x32_bf16 v[36:39], v[216:219], v[168:171], v[36:39]
	v_mfma_f32_16x16x32_bf16 v[32:35], v[224:227], v[168:171], v[32:35]
	v_mfma_f32_16x16x32_bf16 v[20:23], v[216:219], v[194:197], v[20:23]
	v_mfma_f32_16x16x32_bf16 v[16:19], v[224:227], v[194:197], v[16:19]
	v_mfma_f32_16x16x32_bf16 v[4:7], v[216:219], v[208:211], v[4:7]
	v_mfma_f32_16x16x32_bf16 v[0:3], v[224:227], v[208:211], v[0:3]
	s_add_i32 s34, 0, 0x18000
	v_add_u32_e32 v152, s34, v174
	s_barrier
	ds_read_b128 v[140:143], v152
	ds_read_b128 v[144:147], v152 offset:1024
	ds_read_b128 v[148:151], v152 offset:2048
	ds_read_b128 v[152:155], v152 offset:3072
	s_add_u32 s24, s24, 0x80000
	s_addc_u32 s25, s25, 0
	s_mov_b32 m0, s33
	v_lshl_add_u64 v[212:213], s[24:25], 0, v[128:129]
	ds_read_b128 v[156:159], v189 offset:32768
	ds_read_b128 v[160:163], v189 offset:33792
	ds_read_b128 v[164:167], v189 offset:34816
	ds_read_b128 v[168:171], v189 offset:35840
	ds_read_b128 v[190:193], v189 offset:36864
	ds_read_b128 v[194:197], v189 offset:37888
	ds_read_b128 v[198:201], v189 offset:38912
	ds_read_b128 v[208:211], v189 offset:39936
	global_load_lds_dwordx4 v[212:213], off
	v_lshl_add_u64 v[212:213], s[24:25], 0, v[132:133]
	s_mov_b32 m0, s37
	s_nop 0
	global_load_lds_dwordx4 v[212:213], off
	s_waitcnt lgkmcnt(0)
	s_barrier
	v_mfma_f32_16x16x32_bf16 v[124:127], v[140:143], v[156:159], v[124:127]
	v_mfma_f32_16x16x32_bf16 v[120:123], v[148:151], v[156:159], v[120:123]
	v_mfma_f32_16x16x32_bf16 v[108:111], v[140:143], v[164:167], v[108:111]
	v_mfma_f32_16x16x32_bf16 v[104:107], v[148:151], v[164:167], v[104:107]
	v_mfma_f32_16x16x32_bf16 v[92:95], v[140:143], v[190:193], v[92:95]
	v_mfma_f32_16x16x32_bf16 v[88:91], v[148:151], v[190:193], v[88:91]
	v_mfma_f32_16x16x32_bf16 v[76:79], v[140:143], v[198:201], v[76:79]
	v_mfma_f32_16x16x32_bf16 v[72:75], v[148:151], v[198:201], v[72:75]
	v_mfma_f32_16x16x32_bf16 v[124:127], v[144:147], v[160:163], v[124:127]
	v_mfma_f32_16x16x32_bf16 v[120:123], v[152:155], v[160:163], v[120:123]
	v_mfma_f32_16x16x32_bf16 v[108:111], v[144:147], v[168:171], v[108:111]
	v_mfma_f32_16x16x32_bf16 v[104:107], v[152:155], v[168:171], v[104:107]
	v_mfma_f32_16x16x32_bf16 v[92:95], v[144:147], v[194:197], v[92:95]
	v_mfma_f32_16x16x32_bf16 v[88:91], v[152:155], v[194:197], v[88:91]
	v_mfma_f32_16x16x32_bf16 v[76:79], v[144:147], v[208:211], v[76:79]
	v_mfma_f32_16x16x32_bf16 v[72:75], v[152:155], v[208:211], v[72:75]
	s_barrier
	s_add_i32 s24, 0, 0x1c000
	s_add_i32 s25, s34, s28
	v_add_u32_e32 v176, s24, v174
	v_lshl_add_u64 v[180:181], v[180:181], 0, s[40:41]
	s_mov_b32 m0, s25
	ds_read_b128 v[212:215], v176
	ds_read_b128 v[216:219], v176 offset:1024
	ds_read_b128 v[220:223], v176 offset:2048
	ds_read_b128 v[224:227], v176 offset:3072
	global_load_lds_dwordx4 v[180:181], off
	v_lshl_add_u64 v[180:181], v[228:229], 0, s[40:41]
	s_add_i32 m0, s25, 0x2000
	s_nop 0
	global_load_lds_dwordx4 v[180:181], off
	s_waitcnt lgkmcnt(0)
	s_barrier
	v_mfma_f32_16x16x32_bf16 v[116:119], v[212:215], v[156:159], v[116:119]
	v_mfma_f32_16x16x32_bf16 v[112:115], v[220:223], v[156:159], v[112:115]
	v_mfma_f32_16x16x32_bf16 v[100:103], v[212:215], v[164:167], v[100:103]
	v_mfma_f32_16x16x32_bf16 v[96:99], v[220:223], v[164:167], v[96:99]
	v_mfma_f32_16x16x32_bf16 v[84:87], v[212:215], v[190:193], v[84:87]
	v_mfma_f32_16x16x32_bf16 v[80:83], v[220:223], v[190:193], v[80:83]
	v_mfma_f32_16x16x32_bf16 v[68:71], v[212:215], v[198:201], v[68:71]
	v_mfma_f32_16x16x32_bf16 v[64:67], v[220:223], v[198:201], v[64:67]
	v_mfma_f32_16x16x32_bf16 v[116:119], v[216:219], v[160:163], v[116:119]
	v_mfma_f32_16x16x32_bf16 v[112:115], v[224:227], v[160:163], v[112:115]
	v_mfma_f32_16x16x32_bf16 v[100:103], v[216:219], v[168:171], v[100:103]
	v_mfma_f32_16x16x32_bf16 v[96:99], v[224:227], v[168:171], v[96:99]
	v_mfma_f32_16x16x32_bf16 v[84:87], v[216:219], v[194:197], v[84:87]
	v_mfma_f32_16x16x32_bf16 v[80:83], v[224:227], v[194:197], v[80:83]
	v_mfma_f32_16x16x32_bf16 v[68:71], v[216:219], v[208:211], v[68:71]
	v_mfma_f32_16x16x32_bf16 v[64:67], v[224:227], v[208:211], v[64:67]
	s_mov_b32 m0, s47
	v_lshl_add_u64 v[180:181], v[230:231], 0, s[40:41]
	s_barrier
	ds_read_b128 v[156:159], v189 offset:49152
	ds_read_b128 v[160:163], v189 offset:50176
	ds_read_b128 v[164:167], v189 offset:51200
	ds_read_b128 v[168:171], v189 offset:52224
	ds_read_b128 v[190:193], v189 offset:53248
	ds_read_b128 v[194:197], v189 offset:54272
	ds_read_b128 v[198:201], v189 offset:55296
	ds_read_b128 v[208:211], v189 offset:56320
	global_load_lds_dwordx4 v[180:181], off
	v_lshl_add_u64 v[180:181], v[232:233], 0, s[40:41]
	s_mov_b32 m0, s48
	s_nop 0
	global_load_lds_dwordx4 v[180:181], off
	s_waitcnt lgkmcnt(0)
	s_barrier
	v_mfma_f32_16x16x32_bf16 v[60:63], v[140:143], v[156:159], v[60:63]
	v_mfma_f32_16x16x32_bf16 v[56:59], v[148:151], v[156:159], v[56:59]
	v_mfma_f32_16x16x32_bf16 v[44:47], v[140:143], v[164:167], v[44:47]
	v_mfma_f32_16x16x32_bf16 v[40:43], v[148:151], v[164:167], v[40:43]
	v_mfma_f32_16x16x32_bf16 v[28:31], v[140:143], v[190:193], v[28:31]
	v_mfma_f32_16x16x32_bf16 v[24:27], v[148:151], v[190:193], v[24:27]
	v_mfma_f32_16x16x32_bf16 v[12:15], v[140:143], v[198:201], v[12:15]
	v_mfma_f32_16x16x32_bf16 v[8:11], v[148:151], v[198:201], v[8:11]
	v_mfma_f32_16x16x32_bf16 v[60:63], v[144:147], v[160:163], v[60:63]
	v_mfma_f32_16x16x32_bf16 v[56:59], v[152:155], v[160:163], v[56:59]
	v_mfma_f32_16x16x32_bf16 v[44:47], v[144:147], v[168:171], v[44:47]
	v_mfma_f32_16x16x32_bf16 v[40:43], v[152:155], v[168:171], v[40:43]
	v_mfma_f32_16x16x32_bf16 v[28:31], v[144:147], v[194:197], v[28:31]
	v_mfma_f32_16x16x32_bf16 v[24:27], v[152:155], v[194:197], v[24:27]
	v_mfma_f32_16x16x32_bf16 v[12:15], v[144:147], v[208:211], v[12:15]
	v_mfma_f32_16x16x32_bf16 v[8:11], v[152:155], v[208:211], v[8:11]
	s_barrier
	s_add_u32 s20, s20, 0x80080
	s_addc_u32 s21, s21, 0
	s_add_i32 s24, s24, s28
	v_lshl_add_u64 v[140:141], s[20:21], 0, v[130:131]
	s_mov_b32 m0, s24
	s_nop 0
	global_load_lds_dwordx4 v[140:141], off
	v_lshl_add_u64 v[140:141], s[20:21], 0, v[134:135]
	s_add_i32 m0, s24, 0x2000
	s_nop 0
	global_load_lds_dwordx4 v[140:141], off
	s_waitcnt vmcnt(6)
	s_barrier
	v_mfma_f32_16x16x32_bf16 v[52:55], v[212:215], v[156:159], v[52:55]
	v_mfma_f32_16x16x32_bf16 v[48:51], v[220:223], v[156:159], v[48:51]
	v_mfma_f32_16x16x32_bf16 v[36:39], v[212:215], v[164:167], v[36:39]
	v_mfma_f32_16x16x32_bf16 v[32:35], v[220:223], v[164:167], v[32:35]
	v_mfma_f32_16x16x32_bf16 v[20:23], v[212:215], v[190:193], v[20:23]
	v_mfma_f32_16x16x32_bf16 v[16:19], v[220:223], v[190:193], v[16:19]
	v_mfma_f32_16x16x32_bf16 v[4:7], v[212:215], v[198:201], v[4:7]
	v_mfma_f32_16x16x32_bf16 v[0:3], v[220:223], v[198:201], v[0:3]
	v_mfma_f32_16x16x32_bf16 v[52:55], v[216:219], v[160:163], v[52:55]
	v_mfma_f32_16x16x32_bf16 v[48:51], v[224:227], v[160:163], v[48:51]
	v_mfma_f32_16x16x32_bf16 v[36:39], v[216:219], v[168:171], v[36:39]
	v_mfma_f32_16x16x32_bf16 v[32:35], v[224:227], v[168:171], v[32:35]
	v_mfma_f32_16x16x32_bf16 v[20:23], v[216:219], v[194:197], v[20:23]
	v_mfma_f32_16x16x32_bf16 v[16:19], v[224:227], v[194:197], v[16:19]
	v_mfma_f32_16x16x32_bf16 v[4:7], v[216:219], v[208:211], v[4:7]
	v_mfma_f32_16x16x32_bf16 v[0:3], v[224:227], v[208:211], v[0:3]
	s_add_i32 s54, s54, 2
	s_add_u32 s44, s44, 0x100
	s_addc_u32 s53, s53, 0
	s_add_u32 s18, s18, 0x100
	s_addc_u32 s19, s19, 0
	s_cmp_gt_u32 s54, 29
	s_barrier
	s_cbranch_scc0 .LBB0_656
	s_lshl_b32 s5, s16, 8
	s_cmp_lt_i32 s14, 18
	v_readlane_b32 s20, v255, 32
	s_cselect_b64 s[18:19], -1, 0
	v_readlane_b32 s21, v255, 33
	s_or_b64 s[20:21], s[20:21], s[18:19]
	s_mov_b64 s[18:19], -1
	s_and_b64 vcc, exec, s[20:21]
	v_mov_b32_e32 v198, 0xbf1f24be
	s_cbranch_vccnz .LBB0_664
	s_sub_i32 s9, s14, 18
	s_cmp_gt_i32 s16, 31
	s_cbranch_scc0 .LBB0_660
	s_sub_i32 s15, s16, 32
	s_lshr_b32 s15, s15, 1
	s_and_b32 s15, s15, 0x1fffffc
	s_add_i32 s15, s15, s9
	s_lshl_b32 s44, s15, 7
	s_lshl_b64 s[18:19], s[44:45], 13
	s_add_u32 s24, s38, s18
	s_addc_u32 s25, s39, s19
	s_and_b32 s15, s5, 0x700
	s_add_i32 s15, s15, s46
	s_mov_b64 s[18:19], 0
